# M1 log-decay dot products: W/bias readlanes spread over 5 dead SGPRs (CFG liveness) and hoisted above their fmac, removing 217 wait-state s_nops
# baseline (speedup 1.0000x reference)
; template <bool PHC>
; __device__ __forceinline__ void gla_pair(const KPD& kp, int l, int pair, unsigned char* lds, int tid, int lane, int wave, v4u& pz0, v4u& pz1, v4u& pw0, v4u& pw1, int next_pair) {
;     ...
;     const int wvv[6] = {(int)pw0.x, (int)pw0.y, (int)pw0.z, (int)pw0.w, (int)pw1.x, (int)pw1.y};
;     const int bvv = (int)pw1.z;
;     float bc[24], tot[24];
; #pragma unroll
;     for (int c = 0; c < 24; ++c) {
;         float pre = __int_as_float(__builtin_amdgcn_readlane(bvv, c));
; #pragma unroll
;         for (int r = 0; r < 16; ++r) pre += z[r] * __int_as_float(__builtin_amdgcn_readlane(wvv[(24 * r + c) >> 6], (24 * r + c) & 63));
;         const float la = (fminf(pre, 0.f) - __logf(1.f + __expf(-fabsf(pre)))) * (1.f / 16.f);
;         const float inc = wave_incl_scan(la);
;         const float total = __int_as_float(__builtin_amdgcn_readlane(__float_as_int(inc), 63));
;         bc[c] = dir ? (total - inc + la) : inc; tot[c] = total;
.LBB0_264:
	ds_read_b64 v[250:251], v204
	v_readfirstlane_b32 vcc_lo, v225
	s_lshl_b32 vcc_hi, s10, 2
	s_lshr_b32 vcc_lo, vcc_lo, 6
	s_and_b32 vcc_lo, vcc_lo, 3
	s_add_i32 vcc_lo, vcc_lo, vcc_hi
	s_mul_i32 vcc_lo, vcc_lo, 0x1800
	s_waitcnt lgkmcnt(0)
	v_readfirstlane_b32 s100, v250
	v_readfirstlane_b32 s101, v251
	v_mbcnt_lo_u32_b32 v250, -1, 0
	v_mbcnt_hi_u32_b32 v250, -1, v250
	s_add_u32 s100, s100, 0x3400000
	s_addc_u32 s101, s101, 0
	s_add_u32 s100, s100, vcc_lo
	s_addc_u32 s101, s101, 0
	v_lshlrev_b32_e32 v250, 2, v250
	v_add_u32_e32 v251, 0x1000, v250
	ds_read_b64 v[2:3], v204
	s_lshl_b32 s2, s12, 6
	s_and_b32 s46, s10, 3
	s_add_i32 s10, s11, s2
	v_add_u32_e32 v16, s10, v120
	s_waitcnt lgkmcnt(0)
	v_readfirstlane_b32 s3, v3
	v_readfirstlane_b32 s2, v2
	ds_read_b64 v[2:3], v204
	s_add_u32 s2, s2, 0x7800000
	s_addc_u32 s3, s3, 0
	v_mov_b64_e32 v[14:15], s[2:3]
	v_add_u32_e32 v6, s10, v37
	s_waitcnt lgkmcnt(0)
	v_readfirstlane_b32 s47, v3
	v_readfirstlane_b32 s48, v2
	ds_read_b64 v[2:3], v204
	v_add_u32_e32 v10, s10, v121
	v_mad_i64_i32 v[6:7], s[2:3], v6, s33, v[14:15]
	v_mad_i64_i32 v[10:11], s[2:3], v10, s33, v[14:15]
	s_waitcnt lgkmcnt(0)
	v_readfirstlane_b32 s50, v2
	v_add_u32_e32 v2, s10, v33
	v_readfirstlane_b32 s49, v3
	v_mad_i64_i32 v[2:3], s[2:3], v2, s33, v[14:15]
	v_mad_i64_i32 v[14:15], s[2:3], v16, s33, v[14:15]
	s_waitcnt vmcnt(0)
	v_readlane_b32 s32, v32, 0
	v_lshlrev_b32_e32 v64, 16, v18
	v_readlane_b32 s80, v26, 0
	v_mov_b32_e32 v38, s32
	v_and_b32_e32 v63, 0xffff0000, v18
	v_fmac_f32_e32 v38, s80, v64
	v_readlane_b32 s93, v26, 24
	v_lshlrev_b32_e32 v62, 16, v19
	v_and_b32_e32 v61, 0xffff0000, v19
	v_fmac_f32_e32 v38, s93, v63
	v_readlane_b32 s98, v26, 48
	v_lshlrev_b32_e32 v60, 16, v20
	v_and_b32_e32 v59, 0xffff0000, v20
	v_fmac_f32_e32 v38, s98, v62
	v_readlane_b32 s99, v27, 8
	v_lshlrev_b32_e32 v58, 16, v21
	v_and_b32_e32 v57, 0xffff0000, v21
	v_fmac_f32_e32 v38, s99, v61
	v_readlane_b32 s32, v27, 32
	v_lshlrev_b32_e32 v56, 16, v22
	v_and_b32_e32 v55, 0xffff0000, v22
	v_fmac_f32_e32 v38, s32, v60
	v_readlane_b32 s80, v27, 56
	v_lshlrev_b32_e32 v54, 16, v23
	v_and_b32_e32 v53, 0xffff0000, v23
	v_fmac_f32_e32 v38, s80, v59
	v_readlane_b32 s93, v28, 16
	v_lshlrev_b32_e32 v52, 16, v24
	v_and_b32_e32 v34, 0xffff0000, v24
	v_fmac_f32_e32 v38, s93, v58
	v_readlane_b32 s98, v28, 40
	v_readlane_b32 s10, v31, 16
	v_readlane_b32 s11, v31, 40
	v_fmac_f32_e32 v38, s98, v57
	v_readlane_b32 s99, v29, 0
	v_lshlrev_b32_e32 v50, 16, v25
	v_and_b32_e32 v51, 0xffff0000, v25
	v_fmac_f32_e32 v38, s99, v56
	v_readlane_b32 s32, v29, 24
	v_pk_mul_f32 v[66:67], v[50:51], s[10:11]
	s_mov_b32 s72, 0xbfb8aa3b
	v_fmac_f32_e32 v38, s32, v55
	v_readlane_b32 s80, v29, 48
	s_mul_i32 s78, s46, 0xc0
	s_mul_i32 s51, s46, 48
	v_fmac_f32_e32 v38, s80, v54
	v_readlane_b32 s93, v30, 8
	v_lshl_add_u64 v[2:3], v[2:3], 0, s[78:79]
	v_lshl_add_u64 v[6:7], v[6:7], 0, s[78:79]
	v_fmac_f32_e32 v38, s93, v53
	v_readlane_b32 s98, v30, 32
	v_lshl_add_u64 v[10:11], v[10:11], 0, s[78:79]
	s_lshl_b32 s78, s51, 1
	v_fmac_f32_e32 v38, s98, v52
	v_readlane_b32 s99, v30, 56
	v_lshl_add_u64 v[14:15], v[14:15], 0, s[78:79]
	s_lshl_b32 s78, s40, 1
	v_fmac_f32_e32 v38, s99, v34
	v_add_f32_e32 v38, v38, v66
	v_add_f32_e32 v38, v38, v67
	v_min_f32_e32 v65, 0, v38
	v_mul_f32_e64 v38, |v38|, s72
	v_exp_f32_e32 v38, v38
	v_lshl_add_u64 v[46:47], v[14:15], 0, s[78:79]
	s_mov_b32 s78, 0x800000
	s_mov_b32 s87, 0x3f317217
	v_add_f32_e32 v38, 1.0, v38
	v_cmp_gt_f32_e32 vcc, s78, v38
	s_mov_b32 s97, 0x7f800000
	v_readlane_b32 s32, v32, 1
	v_cndmask_b32_e64 v66, 0, 32, vcc
	v_ldexp_f32 v38, v38, v66
	v_log_f32_e32 v38, v38
	v_readlane_b32 s80, v26, 1
	v_mov_b32_e32 v39, s32
	v_readlane_b32 s93, v26, 25
	v_mul_f32_e32 v66, 0x3f317217, v38
	v_fma_f32 v66, v38, s87, -v66
	v_fmac_f32_e32 v66, 0x3377d1cf, v38
	v_fmac_f32_e32 v66, 0x3f317217, v38
	v_cmp_lt_f32_e64 s[10:11], |v38|, s97
	v_fmac_f32_e32 v39, s80, v64
	v_fmac_f32_e32 v39, s93, v63
	v_cndmask_b32_e64 v38, v38, v66, s[10:11]
	v_cndmask_b32_e32 v66, 0, v222, vcc
	v_sub_f32_e32 v38, v38, v66
	v_sub_f32_e32 v38, v65, v38
	v_mul_f32_e32 v65, 0x3d800000, v38
	v_readlane_b32 s98, v26, 49
	v_mov_b32_e32 v66, v35
	v_mov_b32_dpp v65, v65 row_shr:1 row_mask:0xf bank_mask:0xf bound_ctrl:1
	v_fmac_f32_e32 v39, s98, v62
	v_readlane_b32 s99, v27, 9
	v_fmac_f32_e32 v65, 0x3d800000, v38
	v_readlane_b32 s36, v31, 17
	v_fmac_f32_e32 v39, s99, v61
	v_readlane_b32 s32, v27, 33
	v_add_f32_dpp v65, v65, v65 row_shr:2 row_mask:0xf bank_mask:0xf bound_ctrl:1
	v_readlane_b32 s37, v31, 41
	v_fmac_f32_e32 v39, s32, v60
	v_readlane_b32 s80, v27, 57
	v_add_f32_dpp v65, v65, v65 row_shr:4 row_mask:0xf bank_mask:0xf bound_ctrl:1
	v_readlane_b32 s93, v26, 2
	v_fmac_f32_e32 v39, s80, v59
	v_readlane_b32 s98, v28, 17
	v_add_f32_dpp v65, v65, v65 row_shr:8 row_mask:0xf bank_mask:0xf bound_ctrl:1
	v_readlane_b32 s34, v31, 18
	v_fmac_f32_e32 v39, s98, v58
	v_readlane_b32 s99, v28, 41
	v_mov_b32_dpp v66, v65 row_bcast:15 row_mask:0xa bank_mask:0xf
	v_add_f32_e32 v65, v65, v66
	v_fmac_f32_e32 v39, s99, v57
	v_readlane_b32 s32, v29, 1
	v_mov_b32_e32 v66, v35
	v_readlane_b32 s35, v31, 42
	v_fmac_f32_e32 v39, s32, v56
	v_readlane_b32 s80, v29, 25
	v_mov_b32_dpp v66, v65 row_bcast:31 row_mask:0xc bank_mask:0xf
	v_add_f32_e32 v65, v65, v66
	v_fmac_f32_e32 v39, s80, v55
	v_readlane_b32 s98, v29, 49
	v_readlane_b32 s54, v65, 63
	v_pk_mul_f32 v[94:95], v[50:51], s[34:35]
	v_fmac_f32_e32 v39, s98, v54
	v_readlane_b32 s99, v30, 9
	v_sub_f32_e32 v66, s54, v65
	v_fmac_f32_e32 v66, 0x3d800000, v38
	v_fmac_f32_e32 v39, s99, v53
	v_readlane_b32 s32, v30, 33
	v_cndmask_b32_e64 v65, v66, v65, s[0:1]
; template <bool PHC>
; __device__ __forceinline__ void gla_pair(const KPD& kp, int l, int pair, unsigned char* lds, int tid, int lane, int wave, v4u& pz0, v4u& pz1, v4u& pw0, v4u& pw1, int next_pair) {
;     ...
;     for (int c = 0; c < 24; ++c) {
;         float pre = __int_as_float(__builtin_amdgcn_readlane(bvv, c));
; #pragma unroll
;         for (int r = 0; r < 16; ++r) pre += z[r] * __int_as_float(__builtin_amdgcn_readlane(wvv[(24 * r + c) >> 6], (24 * r + c) & 63));
;         const float la = (fminf(pre, 0.f) - __logf(1.f + __expf(-fabsf(pre)))) * (1.f / 16.f);
;         const float inc = wave_incl_scan(la);
;         const float total = __int_as_float(__builtin_amdgcn_readlane(__float_as_int(inc), 63));
;         bc[c] = dir ? (total - inc + la) : inc; tot[c] = total;
	global_store_dword v250, v65, s[100:101]
	v_pk_mul_f32 v[66:67], v[50:51], s[36:37]
	v_fmac_f32_e32 v39, s32, v52
	v_readlane_b32 s80, v30, 57
	v_readlane_b32 s30, v31, 19
	v_readlane_b32 s31, v31, 43
	v_fmac_f32_e32 v39, s80, v34
	v_add_f32_e32 v38, v39, v66
	v_add_f32_e32 v38, v38, v67
	v_min_f32_e32 v39, 0, v38
	v_mul_f32_e64 v38, |v38|, s72
	v_exp_f32_e32 v38, v38
	v_readlane_b32 s98, v32, 2
	v_readlane_b32 s28, v31, 20
	v_readlane_b32 s29, v31, 44
	v_add_f32_e32 v38, 1.0, v38
	v_cmp_gt_f32_e32 vcc, s78, v38
	v_mov_b32_e32 v40, s98
	v_fmac_f32_e32 v40, s93, v64
	v_cndmask_b32_e64 v66, 0, 32, vcc
	v_ldexp_f32 v38, v38, v66
	v_log_f32_e32 v38, v38
	v_readlane_b32 s99, v26, 26
	v_readlane_b32 s32, v26, 3
	v_mov_b32_e32 v79, v35
	v_mul_f32_e32 v66, 0x3f317217, v38
	v_fma_f32 v66, v38, s87, -v66
	v_fmac_f32_e32 v66, 0x3377d1cf, v38
	v_fmac_f32_e32 v66, 0x3f317217, v38
	v_cmp_lt_f32_e64 s[10:11], |v38|, s97
	v_fmac_f32_e32 v40, s99, v63
	v_readlane_b32 s80, v26, 50
	v_cndmask_b32_e64 v38, v38, v66, s[10:11]
	v_cndmask_b32_e32 v66, 0, v222, vcc
	v_sub_f32_e32 v38, v38, v66
	v_sub_f32_e32 v38, v39, v38
	v_fmac_f32_e32 v40, s80, v62
	v_readlane_b32 s93, v27, 10
	v_mul_f32_e32 v39, 0x3d800000, v38
	v_mov_b32_e32 v66, v35
	v_fmac_f32_e32 v40, s93, v61
	v_readlane_b32 s98, v27, 34
	v_mov_b32_dpp v39, v39 row_shr:1 row_mask:0xf bank_mask:0xf bound_ctrl:1
	v_fmac_f32_e32 v39, 0x3d800000, v38
	v_fmac_f32_e32 v40, s98, v60
	v_readlane_b32 s99, v27, 58
	v_add_f32_dpp v39, v39, v39 row_shr:2 row_mask:0xf bank_mask:0xf bound_ctrl:1
	v_lshl_add_u64 v[2:3], v[2:3], 0, v[78:79]
	v_fmac_f32_e32 v40, s99, v59
	v_readlane_b32 s80, v28, 18
	v_add_f32_dpp v39, v39, v39 row_shr:4 row_mask:0xf bank_mask:0xf bound_ctrl:1
	v_readlane_b32 s12, v31, 21
	v_fmac_f32_e32 v40, s80, v58
	v_readlane_b32 s93, v28, 42
	v_add_f32_dpp v39, v39, v39 row_shr:8 row_mask:0xf bank_mask:0xf bound_ctrl:1
	v_readlane_b32 s13, v31, 45
	v_fmac_f32_e32 v40, s93, v57
	v_readlane_b32 s98, v29, 2
	v_mov_b32_dpp v66, v39 row_bcast:15 row_mask:0xa bank_mask:0xf
	v_add_f32_e32 v39, v39, v66
	v_fmac_f32_e32 v40, s98, v56
	v_readlane_b32 s99, v29, 26
	v_mov_b32_e32 v66, v35
	v_mov_b32_e32 v81, v35
	v_fmac_f32_e32 v40, s99, v55
	v_readlane_b32 s80, v29, 50
	v_mov_b32_dpp v66, v39 row_bcast:31 row_mask:0xc bank_mask:0xf
	v_add_f32_e32 v39, v39, v66
	v_fmac_f32_e32 v40, s80, v54
	v_readlane_b32 s93, v30, 10
	v_readlane_b32 s36, v39, 63
	v_lshl_add_u64 v[6:7], v[6:7], 0, v[80:81]
	v_fmac_f32_e32 v40, s93, v53
	v_readlane_b32 s98, v30, 34
	v_sub_f32_e32 v66, s36, v39
	v_fmac_f32_e32 v66, 0x3d800000, v38
	v_fmac_f32_e32 v40, s98, v52
	v_readlane_b32 s99, v30, 58
	v_cndmask_b32_e64 v66, v66, v39, s[0:1]
	global_store_dword v250, v66, s[100:101] offset:256
	v_mov_b32_e32 v83, v35
	v_fmac_f32_e32 v40, s99, v34
	v_add_f32_e32 v38, v40, v94
	v_add_f32_e32 v38, v38, v95
	v_min_f32_e32 v39, 0, v38
	v_mul_f32_e64 v38, |v38|, s72
	v_exp_f32_e32 v38, v38
	v_readlane_b32 s80, v32, 3
	v_pk_mul_f32 v[94:95], v[50:51], s[30:31]
	v_lshl_add_u64 v[10:11], v[10:11], 0, v[82:83]
	v_add_f32_e32 v38, 1.0, v38
	v_cmp_gt_f32_e32 vcc, s78, v38
	v_mov_b32_e32 v41, s80
	v_fmac_f32_e32 v41, s32, v64
	v_cndmask_b32_e64 v40, 0, 32, vcc
	v_ldexp_f32 v38, v38, v40
	v_log_f32_e32 v38, v38
	v_readlane_b32 s93, v26, 27
	v_readlane_b32 s98, v26, 4
	global_load_dwordx4 v[2:5], v[2:3], off offset:768
	v_mul_f32_e32 v40, 0x3f317217, v38
	v_fma_f32 v40, v38, s87, -v40
	v_fmac_f32_e32 v40, 0x3377d1cf, v38
	v_fmac_f32_e32 v40, 0x3f317217, v38
	v_cmp_lt_f32_e64 s[10:11], |v38|, s97
	v_fmac_f32_e32 v41, s93, v63
	v_readlane_b32 s99, v26, 51
	v_cndmask_b32_e64 v38, v38, v40, s[10:11]
	v_cndmask_b32_e32 v40, 0, v222, vcc
	v_sub_f32_e32 v38, v38, v40
	v_sub_f32_e32 v38, v39, v38
	v_fmac_f32_e32 v41, s99, v62
	v_readlane_b32 s32, v27, 11
	v_mul_f32_e32 v39, 0x3d800000, v38
	v_mov_b32_e32 v40, v35
	v_fmac_f32_e32 v41, s32, v61
	v_readlane_b32 s80, v27, 35
	v_mov_b32_dpp v39, v39 row_shr:1 row_mask:0xf bank_mask:0xf bound_ctrl:1
	v_fmac_f32_e32 v39, 0x3d800000, v38
	v_fmac_f32_e32 v41, s80, v60
	v_readlane_b32 s93, v27, 59
	v_add_f32_dpp v39, v39, v39 row_shr:2 row_mask:0xf bank_mask:0xf bound_ctrl:1
	global_load_dwordx4 v[6:9], v[6:7], off offset:768
	v_fmac_f32_e32 v41, s93, v59
	v_readlane_b32 s99, v28, 19
	v_add_f32_dpp v39, v39, v39 row_shr:4 row_mask:0xf bank_mask:0xf bound_ctrl:1
	global_load_dwordx4 v[10:13], v[10:11], off offset:768
	v_fmac_f32_e32 v41, s99, v58
	v_readlane_b32 s32, v28, 43
	v_add_f32_dpp v39, v39, v39 row_shr:8 row_mask:0xf bank_mask:0xf bound_ctrl:1
	global_load_dwordx4 v[14:17], v[46:47], off offset:416
	global_load_dwordx4 v[42:45], v[46:47], off offset:400
	global_load_dwordx4 v[46:49], v[46:47], off offset:384
	v_fmac_f32_e32 v41, s32, v57
	v_readlane_b32 s80, v29, 3
	v_mov_b32_dpp v40, v39 row_bcast:15 row_mask:0xa bank_mask:0xf
	v_add_f32_e32 v39, v39, v40
	v_readlane_b32 s93, v29, 27
	v_fmac_f32_e32 v41, s80, v56
	v_mov_b32_e32 v40, v35
	v_fmac_f32_e32 v41, s93, v55
	v_readlane_b32 s99, v29, 51
	v_mov_b32_dpp v40, v39 row_bcast:31 row_mask:0xc bank_mask:0xf
	v_add_f32_e32 v39, v39, v40
	v_readlane_b32 s32, v30, 11
	v_fmac_f32_e32 v41, s99, v54
	v_readlane_b32 s34, v39, 63
	v_fmac_f32_e32 v41, s32, v53
	v_readlane_b32 s80, v30, 35
	v_sub_f32_e32 v40, s34, v39
	v_fmac_f32_e32 v40, 0x3d800000, v38
	v_fmac_f32_e32 v41, s80, v52
	v_readlane_b32 s93, v30, 59
	v_cndmask_b32_e64 v67, v40, v39, s[0:1]
	global_store_dword v250, v67, s[100:101] offset:512
	v_fmac_f32_e32 v41, s93, v34
	v_add_f32_e32 v38, v41, v94
	v_add_f32_e32 v38, v38, v95
	v_min_f32_e32 v39, 0, v38
	v_mul_f32_e64 v38, |v38|, s72
	v_exp_f32_e32 v38, v38
	v_readlane_b32 s99, v32, 4
	v_pk_mul_f32 v[94:95], v[50:51], s[28:29]
	v_add_f32_e32 v38, 1.0, v38
	v_cmp_gt_f32_e32 vcc, s78, v38
	v_mov_b32_e32 v69, s99
	v_fmac_f32_e32 v69, s98, v64
	v_cndmask_b32_e64 v40, 0, 32, vcc
	v_ldexp_f32 v38, v38, v40
	v_log_f32_e32 v38, v38
	v_readlane_b32 s32, v26, 28
	v_readlane_b32 s80, v26, 5
	v_mul_f32_e32 v40, 0x3f317217, v38
	v_fma_f32 v40, v38, s87, -v40
	v_fmac_f32_e32 v40, 0x3377d1cf, v38
	v_fmac_f32_e32 v40, 0x3f317217, v38
	v_cmp_lt_f32_e64 s[10:11], |v38|, s97
	v_fmac_f32_e32 v69, s32, v63
	v_readlane_b32 s93, v26, 52
	v_cndmask_b32_e64 v38, v38, v40, s[10:11]
	v_cndmask_b32_e32 v40, 0, v222, vcc
	v_sub_f32_e32 v38, v38, v40
	v_sub_f32_e32 v38, v39, v38
	v_fmac_f32_e32 v69, s93, v62
	v_readlane_b32 s98, v27, 12
	v_mul_f32_e32 v39, 0x3d800000, v38
	v_mov_b32_e32 v40, v35
	v_fmac_f32_e32 v69, s98, v61
	v_readlane_b32 s99, v27, 36
	v_mov_b32_dpp v39, v39 row_shr:1 row_mask:0xf bank_mask:0xf bound_ctrl:1
	v_fmac_f32_e32 v39, 0x3d800000, v38
	v_fmac_f32_e32 v69, s99, v60
	v_readlane_b32 s32, v27, 60
	v_add_f32_dpp v39, v39, v39 row_shr:2 row_mask:0xf bank_mask:0xf bound_ctrl:1
	s_waitcnt vmcnt(0)
; template <bool PHC>
; __device__ __forceinline__ void gla_pair(const KPD& kp, int l, int pair, unsigned char* lds, int tid, int lane, int wave, v4u& pz0, v4u& pz1, v4u& pw0, v4u& pw1, int next_pair) {
;     ...
;     for (int c = 0; c < 24; ++c) {
;         float pre = __int_as_float(__builtin_amdgcn_readlane(bvv, c));
; #pragma unroll
;         for (int r = 0; r < 16; ++r) pre += z[r] * __int_as_float(__builtin_amdgcn_readlane(wvv[(24 * r + c) >> 6], (24 * r + c) & 63));
;         const float la = (fminf(pre, 0.f) - __logf(1.f + __expf(-fabsf(pre)))) * (1.f / 16.f);
;         const float inc = wave_incl_scan(la);
;         const float total = __int_as_float(__builtin_amdgcn_readlane(__float_as_int(inc), 63));
;         bc[c] = dir ? (total - inc + la) : inc; tot[c] = total;
	v_lshlrev_b32_e32 v41, 16, v47
	v_readlane_b32 s93, v28, 20
	v_fmac_f32_e32 v69, s32, v59
	v_add_f32_dpp v39, v39, v39 row_shr:4 row_mask:0xf bank_mask:0xf bound_ctrl:1
	v_readlane_b32 s98, v28, 44
	v_fmac_f32_e32 v69, s93, v58
	v_add_f32_dpp v39, v39, v39 row_shr:8 row_mask:0xf bank_mask:0xf bound_ctrl:1
	v_fmac_f32_e32 v69, s98, v57
	v_readlane_b32 s99, v29, 4
	v_mov_b32_dpp v40, v39 row_bcast:15 row_mask:0xa bank_mask:0xf
	v_add_f32_e32 v39, v39, v40
	v_readlane_b32 s32, v29, 28
	v_fmac_f32_e32 v69, s99, v56
	v_mov_b32_e32 v40, v35
	v_fmac_f32_e32 v69, s32, v55
	v_readlane_b32 s93, v29, 52
	v_mov_b32_dpp v40, v39 row_bcast:31 row_mask:0xc bank_mask:0xf
	v_add_f32_e32 v39, v39, v40
	v_readlane_b32 s98, v30, 12
	v_fmac_f32_e32 v69, s93, v54
	v_readlane_b32 s30, v39, 63
	v_fmac_f32_e32 v69, s98, v53
	v_readlane_b32 s99, v30, 36
	v_sub_f32_e32 v40, s30, v39
	v_fmac_f32_e32 v40, 0x3d800000, v38
	v_fmac_f32_e32 v69, s99, v52
	v_readlane_b32 s32, v30, 60
	v_cndmask_b32_e64 v68, v40, v39, s[0:1]
	global_store_dword v250, v68, s[100:101] offset:768
	v_fmac_f32_e32 v69, s32, v34
	v_add_f32_e32 v38, v69, v94
	v_add_f32_e32 v38, v38, v95
	v_min_f32_e32 v39, 0, v38
	v_mul_f32_e64 v38, |v38|, s72
	v_exp_f32_e32 v38, v38
	v_readlane_b32 s93, v32, 5
	v_pk_mul_f32 v[94:95], v[50:51], s[12:13]
	v_add_f32_e32 v38, 1.0, v38
	v_cmp_gt_f32_e32 vcc, s78, v38
	v_mov_b32_e32 v79, s93
	v_fmac_f32_e32 v79, s80, v64
	v_cndmask_b32_e64 v40, 0, 32, vcc
	v_ldexp_f32 v38, v38, v40
	v_log_f32_e32 v38, v38
	v_readlane_b32 s98, v26, 29
	v_readlane_b32 s99, v26, 6
	v_mul_f32_e32 v40, 0x3f317217, v38
	v_fma_f32 v40, v38, s87, -v40
	v_fmac_f32_e32 v40, 0x3377d1cf, v38
	v_fmac_f32_e32 v40, 0x3f317217, v38
	v_cmp_lt_f32_e64 s[10:11], |v38|, s97
	v_fmac_f32_e32 v79, s98, v63
	v_readlane_b32 s32, v26, 53
	v_cndmask_b32_e64 v38, v38, v40, s[10:11]
	v_cndmask_b32_e32 v40, 0, v222, vcc
	v_sub_f32_e32 v38, v38, v40
	v_sub_f32_e32 v38, v39, v38
	v_fmac_f32_e32 v79, s32, v62
	v_readlane_b32 s80, v27, 13
	v_mul_f32_e32 v39, 0x3d800000, v38
	v_mov_b32_e32 v40, v35
	v_fmac_f32_e32 v79, s80, v61
	v_readlane_b32 s93, v27, 37
	v_mov_b32_dpp v39, v39 row_shr:1 row_mask:0xf bank_mask:0xf bound_ctrl:1
	v_fmac_f32_e32 v39, 0x3d800000, v38
	v_readlane_b32 s98, v27, 61
	v_fmac_f32_e32 v79, s93, v60
	v_add_f32_dpp v39, v39, v39 row_shr:2 row_mask:0xf bank_mask:0xf bound_ctrl:1
	v_readlane_b32 s32, v28, 21
	v_fmac_f32_e32 v79, s98, v59
	v_add_f32_dpp v39, v39, v39 row_shr:4 row_mask:0xf bank_mask:0xf bound_ctrl:1
	v_readlane_b32 s80, v28, 45
	v_fmac_f32_e32 v79, s32, v58
	v_add_f32_dpp v39, v39, v39 row_shr:8 row_mask:0xf bank_mask:0xf bound_ctrl:1
	v_fmac_f32_e32 v79, s80, v57
	v_readlane_b32 s93, v29, 5
	v_mov_b32_dpp v40, v39 row_bcast:15 row_mask:0xa bank_mask:0xf
	v_add_f32_e32 v39, v39, v40
	v_readlane_b32 s98, v29, 29
	v_fmac_f32_e32 v79, s93, v56
	v_mov_b32_e32 v40, v35
	v_fmac_f32_e32 v79, s98, v55
	v_readlane_b32 s32, v29, 53
	v_mov_b32_dpp v40, v39 row_bcast:31 row_mask:0xc bank_mask:0xf
	v_add_f32_e32 v39, v39, v40
	v_readlane_b32 s80, v30, 13
	v_fmac_f32_e32 v79, s32, v54
	v_readlane_b32 s28, v39, 63
	v_fmac_f32_e32 v79, s80, v53
	v_readlane_b32 s93, v30, 37
	v_sub_f32_e32 v40, s28, v39
	v_fmac_f32_e32 v40, 0x3d800000, v38
	v_fmac_f32_e32 v79, s93, v52
	v_readlane_b32 s98, v30, 61
	v_cndmask_b32_e64 v69, v40, v39, s[0:1]
	global_store_dword v250, v69, s[100:101] offset:1024
	v_fmac_f32_e32 v79, s98, v34
	v_add_f32_e32 v38, v79, v94
	v_add_f32_e32 v38, v38, v95
	v_min_f32_e32 v39, 0, v38
	v_mul_f32_e64 v38, |v38|, s72
	v_exp_f32_e32 v38, v38
	v_readlane_b32 s32, v32, 6
	v_add_f32_e32 v38, 1.0, v38
	v_cmp_gt_f32_e32 vcc, s78, v38
	v_mov_b32_e32 v81, s32
	v_fmac_f32_e32 v81, s99, v64
	v_cndmask_b32_e64 v40, 0, 32, vcc
	v_ldexp_f32 v38, v38, v40
	v_log_f32_e32 v38, v38
	v_readlane_b32 s80, v26, 30
	v_readlane_b32 s3, v31, 46
	v_mul_f32_e32 v40, 0x3f317217, v38
	v_fma_f32 v40, v38, s87, -v40
	v_fmac_f32_e32 v40, 0x3377d1cf, v38
	v_fmac_f32_e32 v40, 0x3f317217, v38
	v_cmp_lt_f32_e64 s[10:11], |v38|, s97
	v_fmac_f32_e32 v81, s80, v63
	v_readlane_b32 s93, v26, 54
	v_cndmask_b32_e64 v38, v38, v40, s[10:11]
	v_cndmask_b32_e32 v40, 0, v222, vcc
	v_sub_f32_e32 v38, v38, v40
	v_fmac_f32_e32 v81, s93, v62
	v_readlane_b32 s98, v27, 14
	v_sub_f32_e32 v38, v39, v38
	v_mul_f32_e32 v39, 0x3d800000, v38
	v_fmac_f32_e32 v81, s98, v61
	v_readlane_b32 s99, v27, 38
	v_mov_b32_dpp v39, v39 row_shr:1 row_mask:0xf bank_mask:0xf bound_ctrl:1
	v_fmac_f32_e32 v39, 0x3d800000, v38
	v_fmac_f32_e32 v81, s99, v60
	v_readlane_b32 s32, v27, 62
	v_add_f32_dpp v39, v39, v39 row_shr:2 row_mask:0xf bank_mask:0xf bound_ctrl:1
	v_mov_b32_e32 v40, v35
	v_readlane_b32 s80, v28, 22
	v_fmac_f32_e32 v81, s32, v59
	v_add_f32_dpp v39, v39, v39 row_shr:4 row_mask:0xf bank_mask:0xf bound_ctrl:1
	v_readlane_b32 s93, v28, 46
	v_fmac_f32_e32 v81, s80, v58
	v_add_f32_dpp v39, v39, v39 row_shr:8 row_mask:0xf bank_mask:0xf bound_ctrl:1
	v_fmac_f32_e32 v81, s93, v57
	v_readlane_b32 s98, v29, 6
	v_mov_b32_dpp v40, v39 row_bcast:15 row_mask:0xa bank_mask:0xf
	v_add_f32_e32 v39, v39, v40
	v_readlane_b32 s99, v29, 30
	v_fmac_f32_e32 v81, s98, v56
	v_mov_b32_e32 v40, v35
	v_fmac_f32_e32 v81, s99, v55
	v_readlane_b32 s32, v29, 54
	v_mov_b32_dpp v40, v39 row_bcast:31 row_mask:0xc bank_mask:0xf
	v_add_f32_e32 v39, v39, v40
	v_readlane_b32 s80, v30, 14
	v_fmac_f32_e32 v81, s32, v54
	v_readlane_b32 s29, v39, 63
	v_fmac_f32_e32 v81, s80, v53
	v_readlane_b32 s93, v30, 38
	v_sub_f32_e32 v40, s29, v39
	v_fmac_f32_e32 v40, 0x3d800000, v38
	v_fmac_f32_e32 v81, s93, v52
	v_readlane_b32 s98, v30, 62
	v_cndmask_b32_e64 v79, v40, v39, s[0:1]
; template <bool PHC>
; __device__ __forceinline__ void gla_pair(const KPD& kp, int l, int pair, unsigned char* lds, int tid, int lane, int wave, v4u& pz0, v4u& pz1, v4u& pw0, v4u& pw1, int next_pair) {
;     ...
;     for (int c = 0; c < 24; ++c) {
;         float pre = __int_as_float(__builtin_amdgcn_readlane(bvv, c));
; #pragma unroll
;         for (int r = 0; r < 16; ++r) pre += z[r] * __int_as_float(__builtin_amdgcn_readlane(wvv[(24 * r + c) >> 6], (24 * r + c) & 63));
;         const float la = (fminf(pre, 0.f) - __logf(1.f + __expf(-fabsf(pre)))) * (1.f / 16.f);
;         const float inc = wave_incl_scan(la);
;         const float total = __int_as_float(__builtin_amdgcn_readlane(__float_as_int(inc), 63));
;         bc[c] = dir ? (total - inc + la) : inc; tot[c] = total;
	global_store_dword v250, v79, s[100:101] offset:1280
	v_fmac_f32_e32 v81, s98, v34
	v_readlane_b32 s2, v31, 22
	s_nop 1
	v_pk_mul_f32 v[94:95], v[50:51], s[2:3]
	v_readlane_b32 s99, v32, 7
	v_add_f32_e32 v38, v81, v94
	v_add_f32_e32 v38, v38, v95
	v_min_f32_e32 v39, 0, v38
	v_mul_f32_e64 v38, |v38|, s72
	v_exp_f32_e32 v38, v38
	v_readlane_b32 s32, v26, 7
	v_add_f32_e32 v38, 1.0, v38
	v_cmp_gt_f32_e32 vcc, s78, v38
	s_nop 1
	v_cndmask_b32_e64 v40, 0, 32, vcc
	v_ldexp_f32 v38, v38, v40
	v_log_f32_e32 v38, v38
	s_nop 0
	v_mul_f32_e32 v40, 0x3f317217, v38
	v_fma_f32 v40, v38, s87, -v40
	v_fmac_f32_e32 v40, 0x3377d1cf, v38
	v_fmac_f32_e32 v40, 0x3f317217, v38
	v_cmp_lt_f32_e64 s[10:11], |v38|, s97
	s_nop 1
	v_cndmask_b32_e64 v38, v38, v40, s[10:11]
	v_cndmask_b32_e32 v40, 0, v222, vcc
	v_sub_f32_e32 v38, v38, v40
	v_sub_f32_e32 v38, v39, v38
	v_mul_f32_e32 v39, 0x3d800000, v38
	v_mov_b32_e32 v40, v35
	s_nop 0
	v_mov_b32_dpp v39, v39 row_shr:1 row_mask:0xf bank_mask:0xf bound_ctrl:1
	v_fmac_f32_e32 v39, 0x3d800000, v38
	s_nop 1
	v_add_f32_dpp v39, v39, v39 row_shr:2 row_mask:0xf bank_mask:0xf bound_ctrl:1
	s_nop 1
	v_add_f32_dpp v39, v39, v39 row_shr:4 row_mask:0xf bank_mask:0xf bound_ctrl:1
	s_nop 1
	v_add_f32_dpp v39, v39, v39 row_shr:8 row_mask:0xf bank_mask:0xf bound_ctrl:1
	s_nop 1
	v_mov_b32_dpp v40, v39 row_bcast:15 row_mask:0xa bank_mask:0xf
	v_add_f32_e32 v39, v39, v40
	v_mov_b32_e32 v40, v35
	s_nop 0
	v_mov_b32_dpp v40, v39 row_bcast:31 row_mask:0xc bank_mask:0xf
	v_add_f32_e32 v39, v39, v40
	s_nop 0
	v_readlane_b32 s31, v39, 63
	s_nop 1
	v_sub_f32_e32 v40, s31, v39
	v_fmac_f32_e32 v40, 0x3d800000, v38
	v_mov_b32_e32 v38, s99
	v_fmac_f32_e32 v38, s32, v64
	v_readlane_b32 s80, v26, 31
	v_readlane_b32 s3, v31, 47
	v_cndmask_b32_e64 v81, v40, v39, s[0:1]
	v_readlane_b32 s93, v26, 55
	global_store_dword v250, v81, s[100:101] offset:1536
	v_readlane_b32 s98, v27, 15
	v_fmac_f32_e32 v38, s80, v63
	v_readlane_b32 s99, v27, 39
	v_fmac_f32_e32 v38, s93, v62
	v_readlane_b32 s32, v27, 63
	v_fmac_f32_e32 v38, s98, v61
	v_readlane_b32 s80, v28, 23
	v_fmac_f32_e32 v38, s99, v60
	v_readlane_b32 s93, v28, 47
	v_fmac_f32_e32 v38, s32, v59
	v_readlane_b32 s98, v29, 7
	v_fmac_f32_e32 v38, s80, v58
	v_readlane_b32 s99, v29, 31
	v_fmac_f32_e32 v38, s93, v57
	v_readlane_b32 s32, v29, 55
	v_fmac_f32_e32 v38, s98, v56
	v_readlane_b32 s80, v30, 15
	v_fmac_f32_e32 v38, s99, v55
	v_readlane_b32 s93, v30, 39
	v_fmac_f32_e32 v38, s32, v54
	v_readlane_b32 s98, v30, 63
	v_fmac_f32_e32 v38, s80, v53
	v_fmac_f32_e32 v38, s93, v52
	v_fmac_f32_e32 v38, s98, v34
	v_readlane_b32 s2, v31, 23
	s_nop 1
	v_pk_mul_f32 v[94:95], v[50:51], s[2:3]
	v_readlane_b32 s99, v32, 8
	v_add_f32_e32 v38, v38, v94
	v_add_f32_e32 v38, v38, v95
	v_min_f32_e32 v39, 0, v38
	v_mul_f32_e64 v38, |v38|, s72
	v_exp_f32_e32 v38, v38
	v_readlane_b32 s32, v26, 8
	v_add_f32_e32 v38, 1.0, v38
	v_cmp_gt_f32_e32 vcc, s78, v38
	s_nop 1
	v_cndmask_b32_e64 v40, 0, 32, vcc
	v_ldexp_f32 v38, v38, v40
	v_log_f32_e32 v38, v38
	s_nop 0
	v_mul_f32_e32 v40, 0x3f317217, v38
	v_fma_f32 v40, v38, s87, -v40
	v_fmac_f32_e32 v40, 0x3377d1cf, v38
	v_fmac_f32_e32 v40, 0x3f317217, v38
	v_cmp_lt_f32_e64 s[10:11], |v38|, s97
	s_nop 1
	v_cndmask_b32_e64 v38, v38, v40, s[10:11]
	v_cndmask_b32_e32 v40, 0, v222, vcc
	v_sub_f32_e32 v38, v38, v40
	v_sub_f32_e32 v38, v39, v38
	v_mul_f32_e32 v39, 0x3d800000, v38
	v_mov_b32_e32 v40, v35
	s_nop 0
	v_mov_b32_dpp v39, v39 row_shr:1 row_mask:0xf bank_mask:0xf bound_ctrl:1
	v_fmac_f32_e32 v39, 0x3d800000, v38
	s_nop 1
	v_add_f32_dpp v39, v39, v39 row_shr:2 row_mask:0xf bank_mask:0xf bound_ctrl:1
	s_nop 1
	v_add_f32_dpp v39, v39, v39 row_shr:4 row_mask:0xf bank_mask:0xf bound_ctrl:1
	s_nop 1
	v_add_f32_dpp v39, v39, v39 row_shr:8 row_mask:0xf bank_mask:0xf bound_ctrl:1
	s_nop 1
	v_mov_b32_dpp v40, v39 row_bcast:15 row_mask:0xa bank_mask:0xf
	v_add_f32_e32 v39, v39, v40
	v_mov_b32_e32 v40, v35
	s_nop 0
	v_mov_b32_dpp v40, v39 row_bcast:31 row_mask:0xc bank_mask:0xf
	v_add_f32_e32 v39, v39, v40
	s_nop 0
	v_readlane_b32 s35, v39, 63
	s_nop 1
	v_sub_f32_e32 v40, s35, v39
	v_fmac_f32_e32 v40, 0x3d800000, v38
	v_mov_b32_e32 v38, s99
	v_fmac_f32_e32 v38, s32, v64
	v_readlane_b32 s80, v26, 32
	v_readlane_b32 s3, v31, 48
	v_cndmask_b32_e64 v83, v40, v39, s[0:1]
	v_readlane_b32 s93, v26, 56
	global_store_dword v250, v83, s[100:101] offset:1792
	v_readlane_b32 s98, v27, 16
	v_fmac_f32_e32 v38, s80, v63
	v_readlane_b32 s99, v27, 40
	v_fmac_f32_e32 v38, s93, v62
	v_readlane_b32 s32, v28, 0
	v_fmac_f32_e32 v38, s98, v61
	v_readlane_b32 s80, v28, 24
	v_fmac_f32_e32 v38, s99, v60
	v_readlane_b32 s93, v28, 48
	v_fmac_f32_e32 v38, s32, v59
	v_readlane_b32 s98, v29, 8
	v_fmac_f32_e32 v38, s80, v58
	v_readlane_b32 s99, v29, 32
	v_fmac_f32_e32 v38, s93, v57
	v_readlane_b32 s32, v29, 56
	v_fmac_f32_e32 v38, s98, v56
	v_readlane_b32 s80, v30, 16
	v_fmac_f32_e32 v38, s99, v55
	v_readlane_b32 s93, v30, 40
	v_fmac_f32_e32 v38, s32, v54
	v_readlane_b32 s98, v31, 0
	v_fmac_f32_e32 v38, s80, v53
	v_fmac_f32_e32 v38, s93, v52
	v_fmac_f32_e32 v38, s98, v34
	v_readlane_b32 s2, v31, 24
	s_nop 1
	v_pk_mul_f32 v[94:95], v[50:51], s[2:3]
	v_readlane_b32 s99, v32, 9
	v_add_f32_e32 v38, v38, v94
	v_add_f32_e32 v38, v38, v95
	v_min_f32_e32 v39, 0, v38
	v_mul_f32_e64 v38, |v38|, s72
	v_exp_f32_e32 v38, v38
	v_readlane_b32 s32, v26, 9
	v_add_f32_e32 v38, 1.0, v38
	v_cmp_gt_f32_e32 vcc, s78, v38
	s_nop 1
	v_cndmask_b32_e64 v40, 0, 32, vcc
	v_ldexp_f32 v38, v38, v40
	v_log_f32_e32 v38, v38
	s_nop 0
	v_mul_f32_e32 v40, 0x3f317217, v38
	v_fma_f32 v40, v38, s87, -v40
	v_fmac_f32_e32 v40, 0x3377d1cf, v38
	v_fmac_f32_e32 v40, 0x3f317217, v38
; template <bool PHC>
; __device__ __forceinline__ void gla_pair(const KPD& kp, int l, int pair, unsigned char* lds, int tid, int lane, int wave, v4u& pz0, v4u& pz1, v4u& pw0, v4u& pw1, int next_pair) {
;     ...
;     for (int c = 0; c < 24; ++c) {
;         float pre = __int_as_float(__builtin_amdgcn_readlane(bvv, c));
; #pragma unroll
;         for (int r = 0; r < 16; ++r) pre += z[r] * __int_as_float(__builtin_amdgcn_readlane(wvv[(24 * r + c) >> 6], (24 * r + c) & 63));
;         const float la = (fminf(pre, 0.f) - __logf(1.f + __expf(-fabsf(pre)))) * (1.f / 16.f);
;         const float inc = wave_incl_scan(la);
;         const float total = __int_as_float(__builtin_amdgcn_readlane(__float_as_int(inc), 63));
;         bc[c] = dir ? (total - inc + la) : inc; tot[c] = total;
	v_cmp_lt_f32_e64 s[10:11], |v38|, s97
	s_nop 1
	v_cndmask_b32_e64 v38, v38, v40, s[10:11]
	v_cndmask_b32_e32 v40, 0, v222, vcc
	v_sub_f32_e32 v38, v38, v40
	v_sub_f32_e32 v38, v39, v38
	v_mul_f32_e32 v39, 0x3d800000, v38
	v_mov_b32_e32 v40, v35
	s_nop 0
	v_mov_b32_dpp v39, v39 row_shr:1 row_mask:0xf bank_mask:0xf bound_ctrl:1
	v_fmac_f32_e32 v39, 0x3d800000, v38
	s_nop 1
	v_add_f32_dpp v39, v39, v39 row_shr:2 row_mask:0xf bank_mask:0xf bound_ctrl:1
	s_nop 1
	v_add_f32_dpp v39, v39, v39 row_shr:4 row_mask:0xf bank_mask:0xf bound_ctrl:1
	s_nop 1
	v_add_f32_dpp v39, v39, v39 row_shr:8 row_mask:0xf bank_mask:0xf bound_ctrl:1
	s_nop 1
	v_mov_b32_dpp v40, v39 row_bcast:15 row_mask:0xa bank_mask:0xf
	v_add_f32_e32 v39, v39, v40
	v_mov_b32_e32 v40, v35
	s_nop 0
	v_mov_b32_dpp v40, v39 row_bcast:31 row_mask:0xc bank_mask:0xf
	v_add_f32_e32 v39, v39, v40
	s_nop 0
	v_readlane_b32 s37, v39, 63
	s_nop 1
	v_sub_f32_e32 v40, s37, v39
	v_fmac_f32_e32 v40, 0x3d800000, v38
	v_mov_b32_e32 v38, s99
	v_fmac_f32_e32 v38, s32, v64
	v_readlane_b32 s80, v26, 33
	v_readlane_b32 s3, v31, 49
	v_cndmask_b32_e64 v85, v40, v39, s[0:1]
	v_readlane_b32 s93, v26, 57
	global_store_dword v250, v85, s[100:101] offset:2048
	v_readlane_b32 s98, v27, 17
	v_fmac_f32_e32 v38, s80, v63
	v_readlane_b32 s99, v27, 41
	v_fmac_f32_e32 v38, s93, v62
	v_readlane_b32 s32, v28, 1
	v_fmac_f32_e32 v38, s98, v61
	v_readlane_b32 s80, v28, 25
	v_fmac_f32_e32 v38, s99, v60
	v_readlane_b32 s93, v28, 49
	v_fmac_f32_e32 v38, s32, v59
	v_readlane_b32 s98, v29, 9
	v_fmac_f32_e32 v38, s80, v58
	v_readlane_b32 s99, v29, 33
	v_fmac_f32_e32 v38, s93, v57
	v_readlane_b32 s32, v29, 57
	v_fmac_f32_e32 v38, s98, v56
	v_readlane_b32 s80, v30, 17
	v_fmac_f32_e32 v38, s99, v55
	v_readlane_b32 s93, v30, 41
	v_fmac_f32_e32 v38, s32, v54
	v_readlane_b32 s98, v31, 1
	v_fmac_f32_e32 v38, s80, v53
	v_fmac_f32_e32 v38, s93, v52
	v_fmac_f32_e32 v38, s98, v34
	v_readlane_b32 s2, v31, 25
	s_nop 1
	v_pk_mul_f32 v[94:95], v[50:51], s[2:3]
	v_readlane_b32 s99, v32, 10
	v_add_f32_e32 v38, v38, v94
	v_add_f32_e32 v38, v38, v95
	v_min_f32_e32 v39, 0, v38
	v_mul_f32_e64 v38, |v38|, s72
	v_exp_f32_e32 v38, v38
	v_readlane_b32 s32, v26, 10
	v_add_f32_e32 v38, 1.0, v38
	v_cmp_gt_f32_e32 vcc, s78, v38
	s_nop 1
	v_cndmask_b32_e64 v40, 0, 32, vcc
	v_ldexp_f32 v38, v38, v40
	v_log_f32_e32 v38, v38
	s_nop 0
	v_mul_f32_e32 v40, 0x3f317217, v38
	v_fma_f32 v40, v38, s87, -v40
	v_fmac_f32_e32 v40, 0x3377d1cf, v38
	v_fmac_f32_e32 v40, 0x3f317217, v38
	v_cmp_lt_f32_e64 s[10:11], |v38|, s97
	s_nop 1
	v_cndmask_b32_e64 v38, v38, v40, s[10:11]
	v_cndmask_b32_e32 v40, 0, v222, vcc
	v_sub_f32_e32 v38, v38, v40
	v_sub_f32_e32 v38, v39, v38
	v_mul_f32_e32 v39, 0x3d800000, v38
	v_mov_b32_e32 v40, v35
	s_nop 0
	v_mov_b32_dpp v39, v39 row_shr:1 row_mask:0xf bank_mask:0xf bound_ctrl:1
	v_fmac_f32_e32 v39, 0x3d800000, v38
	s_nop 1
	v_add_f32_dpp v39, v39, v39 row_shr:2 row_mask:0xf bank_mask:0xf bound_ctrl:1
	s_nop 1
	v_add_f32_dpp v39, v39, v39 row_shr:4 row_mask:0xf bank_mask:0xf bound_ctrl:1
	s_nop 1
	v_add_f32_dpp v39, v39, v39 row_shr:8 row_mask:0xf bank_mask:0xf bound_ctrl:1
	s_nop 1
	v_mov_b32_dpp v40, v39 row_bcast:15 row_mask:0xa bank_mask:0xf
	v_add_f32_e32 v39, v39, v40
	v_mov_b32_e32 v40, v35
	s_nop 0
	v_mov_b32_dpp v40, v39 row_bcast:31 row_mask:0xc bank_mask:0xf
	v_add_f32_e32 v39, v39, v40
	s_nop 0
	v_readlane_b32 s55, v39, 63
	s_nop 1
	v_sub_f32_e32 v40, s55, v39
	v_fmac_f32_e32 v40, 0x3d800000, v38
	v_mov_b32_e32 v38, s99
	v_fmac_f32_e32 v38, s32, v64
	v_readlane_b32 s80, v26, 34
	v_readlane_b32 s3, v31, 50
	v_cndmask_b32_e64 v87, v40, v39, s[0:1]
	v_readlane_b32 s93, v26, 58
	global_store_dword v250, v87, s[100:101] offset:2304
	v_readlane_b32 s98, v27, 18
	v_fmac_f32_e32 v38, s80, v63
	v_readlane_b32 s99, v27, 42
	v_fmac_f32_e32 v38, s93, v62
	v_readlane_b32 s32, v28, 2
	v_fmac_f32_e32 v38, s98, v61
	v_readlane_b32 s80, v28, 26
	v_fmac_f32_e32 v38, s99, v60
	v_readlane_b32 s93, v28, 50
	v_fmac_f32_e32 v38, s32, v59
	v_readlane_b32 s98, v29, 10
	v_fmac_f32_e32 v38, s80, v58
	v_readlane_b32 s99, v29, 34
	v_fmac_f32_e32 v38, s93, v57
	v_readlane_b32 s32, v29, 58
	v_fmac_f32_e32 v38, s98, v56
	v_readlane_b32 s80, v30, 18
	v_fmac_f32_e32 v38, s99, v55
	v_readlane_b32 s93, v30, 42
	v_fmac_f32_e32 v38, s32, v54
	v_readlane_b32 s98, v31, 2
	v_fmac_f32_e32 v38, s80, v53
	v_fmac_f32_e32 v38, s93, v52
	v_fmac_f32_e32 v38, s98, v34
	v_readlane_b32 s2, v31, 26
	s_nop 1
	v_pk_mul_f32 v[94:95], v[50:51], s[2:3]
	v_readlane_b32 s99, v32, 11
	v_add_f32_e32 v38, v38, v94
	v_add_f32_e32 v38, v38, v95
	v_min_f32_e32 v39, 0, v38
	v_mul_f32_e64 v38, |v38|, s72
	v_exp_f32_e32 v38, v38
	v_readlane_b32 s32, v26, 11
	v_add_f32_e32 v38, 1.0, v38
	v_cmp_gt_f32_e32 vcc, s78, v38
	s_nop 1
	v_cndmask_b32_e64 v40, 0, 32, vcc
	v_ldexp_f32 v38, v38, v40
	v_log_f32_e32 v38, v38
	s_nop 0
	v_mul_f32_e32 v40, 0x3f317217, v38
	v_fma_f32 v40, v38, s87, -v40
	v_fmac_f32_e32 v40, 0x3377d1cf, v38
	v_fmac_f32_e32 v40, 0x3f317217, v38
	v_cmp_lt_f32_e64 s[10:11], |v38|, s97
	s_nop 1
	v_cndmask_b32_e64 v38, v38, v40, s[10:11]
	v_cndmask_b32_e32 v40, 0, v222, vcc
	v_sub_f32_e32 v38, v38, v40
	v_sub_f32_e32 v38, v39, v38
	v_mul_f32_e32 v39, 0x3d800000, v38
	v_mov_b32_e32 v40, v35
	s_nop 0
	v_mov_b32_dpp v39, v39 row_shr:1 row_mask:0xf bank_mask:0xf bound_ctrl:1
	v_fmac_f32_e32 v39, 0x3d800000, v38
	s_nop 1
	v_add_f32_dpp v39, v39, v39 row_shr:2 row_mask:0xf bank_mask:0xf bound_ctrl:1
	s_nop 1
	v_add_f32_dpp v39, v39, v39 row_shr:4 row_mask:0xf bank_mask:0xf bound_ctrl:1
	s_nop 1
	v_add_f32_dpp v39, v39, v39 row_shr:8 row_mask:0xf bank_mask:0xf bound_ctrl:1
	s_nop 1
; template <bool PHC>
; __device__ __forceinline__ void gla_pair(const KPD& kp, int l, int pair, unsigned char* lds, int tid, int lane, int wave, v4u& pz0, v4u& pz1, v4u& pw0, v4u& pw1, int next_pair) {
;     ...
;     for (int c = 0; c < 24; ++c) {
;         float pre = __int_as_float(__builtin_amdgcn_readlane(bvv, c));
; #pragma unroll
;         for (int r = 0; r < 16; ++r) pre += z[r] * __int_as_float(__builtin_amdgcn_readlane(wvv[(24 * r + c) >> 6], (24 * r + c) & 63));
;         const float la = (fminf(pre, 0.f) - __logf(1.f + __expf(-fabsf(pre)))) * (1.f / 16.f);
;         const float inc = wave_incl_scan(la);
;         const float total = __int_as_float(__builtin_amdgcn_readlane(__float_as_int(inc), 63));
;         bc[c] = dir ? (total - inc + la) : inc; tot[c] = total;
	v_mov_b32_dpp v40, v39 row_bcast:15 row_mask:0xa bank_mask:0xf
	v_add_f32_e32 v39, v39, v40
	v_mov_b32_e32 v40, v35
	s_nop 0
	v_mov_b32_dpp v40, v39 row_bcast:31 row_mask:0xc bank_mask:0xf
	v_add_f32_e32 v39, v39, v40
	s_nop 0
	v_readlane_b32 s56, v39, 63
	s_nop 1
	v_sub_f32_e32 v40, s56, v39
	v_fmac_f32_e32 v40, 0x3d800000, v38
	v_mov_b32_e32 v38, s99
	v_fmac_f32_e32 v38, s32, v64
	v_readlane_b32 s80, v26, 35
	v_readlane_b32 s3, v31, 51
	v_cndmask_b32_e64 v89, v40, v39, s[0:1]
	v_readlane_b32 s93, v26, 59
	global_store_dword v250, v89, s[100:101] offset:2560
	v_readlane_b32 s98, v27, 19
	v_fmac_f32_e32 v38, s80, v63
	v_readlane_b32 s99, v27, 43
	v_fmac_f32_e32 v38, s93, v62
	v_readlane_b32 s32, v28, 3
	v_fmac_f32_e32 v38, s98, v61
	v_readlane_b32 s80, v28, 27
	v_fmac_f32_e32 v38, s99, v60
	v_readlane_b32 s93, v28, 51
	v_fmac_f32_e32 v38, s32, v59
	v_readlane_b32 s98, v29, 11
	v_fmac_f32_e32 v38, s80, v58
	v_readlane_b32 s99, v29, 35
	v_fmac_f32_e32 v38, s93, v57
	v_readlane_b32 s32, v29, 59
	v_fmac_f32_e32 v38, s98, v56
	v_readlane_b32 s80, v30, 19
	v_fmac_f32_e32 v38, s99, v55
	v_readlane_b32 s93, v30, 43
	v_fmac_f32_e32 v38, s32, v54
	v_readlane_b32 s98, v31, 3
	v_fmac_f32_e32 v38, s80, v53
	v_fmac_f32_e32 v38, s93, v52
	v_fmac_f32_e32 v38, s98, v34
	v_readlane_b32 s2, v31, 27
	s_nop 1
	v_pk_mul_f32 v[94:95], v[50:51], s[2:3]
	v_readlane_b32 s99, v32, 12
	v_add_f32_e32 v38, v38, v94
	v_add_f32_e32 v38, v38, v95
	v_min_f32_e32 v39, 0, v38
	v_mul_f32_e64 v38, |v38|, s72
	v_exp_f32_e32 v38, v38
	v_readlane_b32 s32, v26, 12
	v_add_f32_e32 v38, 1.0, v38
	v_cmp_gt_f32_e32 vcc, s78, v38
	s_nop 1
	v_cndmask_b32_e64 v40, 0, 32, vcc
	v_ldexp_f32 v38, v38, v40
	v_log_f32_e32 v38, v38
	s_nop 0
	v_mul_f32_e32 v40, 0x3f317217, v38
	v_fma_f32 v40, v38, s87, -v40
	v_fmac_f32_e32 v40, 0x3377d1cf, v38
	v_fmac_f32_e32 v40, 0x3f317217, v38
	v_cmp_lt_f32_e64 s[10:11], |v38|, s97
	s_nop 1
	v_cndmask_b32_e64 v38, v38, v40, s[10:11]
	v_cndmask_b32_e32 v40, 0, v222, vcc
	v_sub_f32_e32 v38, v38, v40
	v_sub_f32_e32 v38, v39, v38
	v_mul_f32_e32 v39, 0x3d800000, v38
	v_mov_b32_e32 v40, v35
	s_nop 0
	v_mov_b32_dpp v39, v39 row_shr:1 row_mask:0xf bank_mask:0xf bound_ctrl:1
	v_fmac_f32_e32 v39, 0x3d800000, v38
	s_nop 1
	v_add_f32_dpp v39, v39, v39 row_shr:2 row_mask:0xf bank_mask:0xf bound_ctrl:1
	s_nop 1
	v_add_f32_dpp v39, v39, v39 row_shr:4 row_mask:0xf bank_mask:0xf bound_ctrl:1
	s_nop 1
	v_add_f32_dpp v39, v39, v39 row_shr:8 row_mask:0xf bank_mask:0xf bound_ctrl:1
	s_nop 1
	v_mov_b32_dpp v40, v39 row_bcast:15 row_mask:0xa bank_mask:0xf
	v_add_f32_e32 v39, v39, v40
	v_mov_b32_e32 v40, v35
	s_nop 0
	v_mov_b32_dpp v40, v39 row_bcast:31 row_mask:0xc bank_mask:0xf
	v_add_f32_e32 v39, v39, v40
	s_nop 0
	v_readlane_b32 s57, v39, 63
	s_nop 1
	v_sub_f32_e32 v40, s57, v39
	v_fmac_f32_e32 v40, 0x3d800000, v38
	v_mov_b32_e32 v38, s99
	v_fmac_f32_e32 v38, s32, v64
	v_readlane_b32 s80, v26, 36
	v_readlane_b32 s3, v31, 52
	v_cndmask_b32_e64 v91, v40, v39, s[0:1]
	v_readlane_b32 s93, v26, 60
	global_store_dword v250, v91, s[100:101] offset:2816
	v_readlane_b32 s98, v27, 20
	v_fmac_f32_e32 v38, s80, v63
	v_readlane_b32 s99, v27, 44
	v_fmac_f32_e32 v38, s93, v62
	v_readlane_b32 s32, v28, 4
	v_fmac_f32_e32 v38, s98, v61
	v_readlane_b32 s80, v28, 28
	v_fmac_f32_e32 v38, s99, v60
	v_readlane_b32 s93, v28, 52
	v_fmac_f32_e32 v38, s32, v59
	v_readlane_b32 s98, v29, 12
	v_fmac_f32_e32 v38, s80, v58
	v_readlane_b32 s99, v29, 36
	v_fmac_f32_e32 v38, s93, v57
	v_readlane_b32 s32, v29, 60
	v_fmac_f32_e32 v38, s98, v56
	v_readlane_b32 s80, v30, 20
	v_fmac_f32_e32 v38, s99, v55
	v_readlane_b32 s93, v30, 44
	v_fmac_f32_e32 v38, s32, v54
	v_readlane_b32 s98, v31, 4
	v_fmac_f32_e32 v38, s80, v53
	v_fmac_f32_e32 v38, s93, v52
	v_fmac_f32_e32 v38, s98, v34
	v_readlane_b32 s2, v31, 28
	s_nop 1
	v_pk_mul_f32 v[94:95], v[50:51], s[2:3]
	v_readlane_b32 s99, v32, 13
	v_add_f32_e32 v38, v38, v94
	v_add_f32_e32 v38, v38, v95
	v_min_f32_e32 v39, 0, v38
	v_mul_f32_e64 v38, |v38|, s72
	v_exp_f32_e32 v38, v38
	v_readlane_b32 s32, v26, 13
	v_add_f32_e32 v38, 1.0, v38
	v_cmp_gt_f32_e32 vcc, s78, v38
	s_nop 1
	v_cndmask_b32_e64 v40, 0, 32, vcc
	v_ldexp_f32 v38, v38, v40
	v_log_f32_e32 v38, v38
	s_nop 0
	v_mul_f32_e32 v40, 0x3f317217, v38
	v_fma_f32 v40, v38, s87, -v40
	v_fmac_f32_e32 v40, 0x3377d1cf, v38
	v_fmac_f32_e32 v40, 0x3f317217, v38
	v_cmp_lt_f32_e64 s[10:11], |v38|, s97
	s_nop 1
	v_cndmask_b32_e64 v38, v38, v40, s[10:11]
	v_cndmask_b32_e32 v40, 0, v222, vcc
	v_sub_f32_e32 v38, v38, v40
	v_sub_f32_e32 v38, v39, v38
	v_mul_f32_e32 v39, 0x3d800000, v38
	v_mov_b32_e32 v40, v35
	s_nop 0
	v_mov_b32_dpp v39, v39 row_shr:1 row_mask:0xf bank_mask:0xf bound_ctrl:1
	v_fmac_f32_e32 v39, 0x3d800000, v38
	s_nop 1
	v_add_f32_dpp v39, v39, v39 row_shr:2 row_mask:0xf bank_mask:0xf bound_ctrl:1
	s_nop 1
	v_add_f32_dpp v39, v39, v39 row_shr:4 row_mask:0xf bank_mask:0xf bound_ctrl:1
	s_nop 1
	v_add_f32_dpp v39, v39, v39 row_shr:8 row_mask:0xf bank_mask:0xf bound_ctrl:1
	s_nop 1
	v_mov_b32_dpp v40, v39 row_bcast:15 row_mask:0xa bank_mask:0xf
	v_add_f32_e32 v39, v39, v40
	v_mov_b32_e32 v40, v35
	s_nop 0
	v_mov_b32_dpp v40, v39 row_bcast:31 row_mask:0xc bank_mask:0xf
	v_add_f32_e32 v39, v39, v40
	s_nop 0
	v_readlane_b32 s59, v39, 63
	s_nop 1
	v_sub_f32_e32 v40, s59, v39
	v_fmac_f32_e32 v40, 0x3d800000, v38
	v_mov_b32_e32 v38, s99
	v_fmac_f32_e32 v38, s32, v64
	v_readlane_b32 s80, v26, 37
	v_readlane_b32 s3, v31, 53
	v_cndmask_b32_e64 v93, v40, v39, s[0:1]
	v_readlane_b32 s93, v26, 61
	global_store_dword v250, v93, s[100:101] offset:3072
	v_readlane_b32 s98, v27, 21
	v_fmac_f32_e32 v38, s80, v63
	v_readlane_b32 s99, v27, 45
; template <bool PHC>
; __device__ __forceinline__ void gla_pair(const KPD& kp, int l, int pair, unsigned char* lds, int tid, int lane, int wave, v4u& pz0, v4u& pz1, v4u& pw0, v4u& pw1, int next_pair) {
;     ...
;     for (int c = 0; c < 24; ++c) {
;         float pre = __int_as_float(__builtin_amdgcn_readlane(bvv, c));
; #pragma unroll
;         for (int r = 0; r < 16; ++r) pre += z[r] * __int_as_float(__builtin_amdgcn_readlane(wvv[(24 * r + c) >> 6], (24 * r + c) & 63));
;         const float la = (fminf(pre, 0.f) - __logf(1.f + __expf(-fabsf(pre)))) * (1.f / 16.f);
;         const float inc = wave_incl_scan(la);
;         const float total = __int_as_float(__builtin_amdgcn_readlane(__float_as_int(inc), 63));
;         bc[c] = dir ? (total - inc + la) : inc; tot[c] = total;
	v_fmac_f32_e32 v38, s93, v62
	v_readlane_b32 s32, v28, 5
	v_fmac_f32_e32 v38, s98, v61
	v_readlane_b32 s80, v28, 29
	v_fmac_f32_e32 v38, s99, v60
	v_readlane_b32 s93, v28, 53
	v_fmac_f32_e32 v38, s32, v59
	v_readlane_b32 s98, v29, 13
	v_fmac_f32_e32 v38, s80, v58
	v_readlane_b32 s99, v29, 37
	v_fmac_f32_e32 v38, s93, v57
	v_readlane_b32 s32, v29, 61
	v_fmac_f32_e32 v38, s98, v56
	v_readlane_b32 s80, v30, 21
	v_fmac_f32_e32 v38, s99, v55
	v_readlane_b32 s93, v30, 45
	v_fmac_f32_e32 v38, s32, v54
	v_readlane_b32 s98, v31, 5
	v_fmac_f32_e32 v38, s80, v53
	v_fmac_f32_e32 v38, s93, v52
	v_fmac_f32_e32 v38, s98, v34
	v_readlane_b32 s2, v31, 29
	s_nop 1
	v_pk_mul_f32 v[94:95], v[50:51], s[2:3]
	v_readlane_b32 s99, v32, 14
	v_add_f32_e32 v38, v38, v94
	v_add_f32_e32 v38, v38, v95
	v_min_f32_e32 v39, 0, v38
	v_mul_f32_e64 v38, |v38|, s72
	v_exp_f32_e32 v38, v38
	v_readlane_b32 s32, v26, 14
	v_add_f32_e32 v38, 1.0, v38
	v_cmp_gt_f32_e32 vcc, s78, v38
	s_nop 1
	v_cndmask_b32_e64 v40, 0, 32, vcc
	v_ldexp_f32 v38, v38, v40
	v_log_f32_e32 v38, v38
	s_nop 0
	v_mul_f32_e32 v40, 0x3f317217, v38
	v_fma_f32 v40, v38, s87, -v40
	v_fmac_f32_e32 v40, 0x3377d1cf, v38
	v_fmac_f32_e32 v40, 0x3f317217, v38
	v_cmp_lt_f32_e64 s[10:11], |v38|, s97
	s_nop 1
	v_cndmask_b32_e64 v38, v38, v40, s[10:11]
	v_cndmask_b32_e32 v40, 0, v222, vcc
	v_sub_f32_e32 v38, v38, v40
	v_sub_f32_e32 v38, v39, v38
	v_mul_f32_e32 v39, 0x3d800000, v38
	v_mov_b32_e32 v40, v35
	s_nop 0
	v_mov_b32_dpp v39, v39 row_shr:1 row_mask:0xf bank_mask:0xf bound_ctrl:1
	v_fmac_f32_e32 v39, 0x3d800000, v38
	s_nop 1
	v_add_f32_dpp v39, v39, v39 row_shr:2 row_mask:0xf bank_mask:0xf bound_ctrl:1
	s_nop 1
	v_add_f32_dpp v39, v39, v39 row_shr:4 row_mask:0xf bank_mask:0xf bound_ctrl:1
	s_nop 1
	v_add_f32_dpp v39, v39, v39 row_shr:8 row_mask:0xf bank_mask:0xf bound_ctrl:1
	s_nop 1
	v_mov_b32_dpp v40, v39 row_bcast:15 row_mask:0xa bank_mask:0xf
	v_add_f32_e32 v39, v39, v40
	v_mov_b32_e32 v40, v35
	s_nop 0
	v_mov_b32_dpp v40, v39 row_bcast:31 row_mask:0xc bank_mask:0xf
	v_add_f32_e32 v39, v39, v40
	s_nop 0
	v_readlane_b32 s60, v39, 63
	s_nop 1
	v_sub_f32_e32 v40, s60, v39
	v_fmac_f32_e32 v40, 0x3d800000, v38
	v_mov_b32_e32 v38, s99
	v_fmac_f32_e32 v38, s32, v64
	v_readlane_b32 s80, v26, 38
	v_readlane_b32 s3, v31, 54
	v_cndmask_b32_e64 v94, v40, v39, s[0:1]
	v_readlane_b32 s93, v26, 62
	global_store_dword v250, v94, s[100:101] offset:3328
	v_readlane_b32 s98, v27, 22
	v_fmac_f32_e32 v38, s80, v63
	v_readlane_b32 s99, v27, 46
	v_fmac_f32_e32 v38, s93, v62
	v_readlane_b32 s32, v28, 6
	v_fmac_f32_e32 v38, s98, v61
	v_readlane_b32 s80, v28, 30
	v_fmac_f32_e32 v38, s99, v60
	v_readlane_b32 s93, v28, 54
	v_fmac_f32_e32 v38, s32, v59
	v_readlane_b32 s98, v29, 14
	v_fmac_f32_e32 v38, s80, v58
	v_readlane_b32 s99, v29, 38
	v_fmac_f32_e32 v38, s93, v57
	v_readlane_b32 s32, v29, 62
	v_fmac_f32_e32 v38, s98, v56
	v_readlane_b32 s80, v30, 22
	v_fmac_f32_e32 v38, s99, v55
	v_readlane_b32 s93, v30, 46
	v_fmac_f32_e32 v38, s32, v54
	v_readlane_b32 s98, v31, 6
	v_fmac_f32_e32 v38, s80, v53
	v_fmac_f32_e32 v38, s93, v52
	v_fmac_f32_e32 v38, s98, v34
	v_readlane_b32 s2, v31, 30
	s_nop 1
	v_pk_mul_f32 v[96:97], v[50:51], s[2:3]
	v_readlane_b32 s99, v32, 15
	v_add_f32_e32 v38, v38, v96
	v_add_f32_e32 v38, v38, v97
	v_min_f32_e32 v39, 0, v38
	v_mul_f32_e64 v38, |v38|, s72
	v_exp_f32_e32 v38, v38
	v_readlane_b32 s32, v26, 15
	v_add_f32_e32 v38, 1.0, v38
	v_cmp_gt_f32_e32 vcc, s78, v38
	s_nop 1
	v_cndmask_b32_e64 v40, 0, 32, vcc
	v_ldexp_f32 v38, v38, v40
	v_log_f32_e32 v38, v38
	s_nop 0
	v_mul_f32_e32 v40, 0x3f317217, v38
	v_fma_f32 v40, v38, s87, -v40
	v_fmac_f32_e32 v40, 0x3377d1cf, v38
	v_fmac_f32_e32 v40, 0x3f317217, v38
	v_cmp_lt_f32_e64 s[10:11], |v38|, s97
	s_nop 1
	v_cndmask_b32_e64 v38, v38, v40, s[10:11]
	v_cndmask_b32_e32 v40, 0, v222, vcc
	v_sub_f32_e32 v38, v38, v40
	v_sub_f32_e32 v38, v39, v38
	v_mul_f32_e32 v39, 0x3d800000, v38
	v_mov_b32_e32 v40, v35
	s_nop 0
	v_mov_b32_dpp v39, v39 row_shr:1 row_mask:0xf bank_mask:0xf bound_ctrl:1
	v_fmac_f32_e32 v39, 0x3d800000, v38
	s_nop 1
	v_add_f32_dpp v39, v39, v39 row_shr:2 row_mask:0xf bank_mask:0xf bound_ctrl:1
	s_nop 1
	v_add_f32_dpp v39, v39, v39 row_shr:4 row_mask:0xf bank_mask:0xf bound_ctrl:1
	s_nop 1
	v_add_f32_dpp v39, v39, v39 row_shr:8 row_mask:0xf bank_mask:0xf bound_ctrl:1
	s_nop 1
	v_mov_b32_dpp v40, v39 row_bcast:15 row_mask:0xa bank_mask:0xf
	v_add_f32_e32 v39, v39, v40
	v_mov_b32_e32 v40, v35
	s_nop 0
	v_mov_b32_dpp v40, v39 row_bcast:31 row_mask:0xc bank_mask:0xf
	v_add_f32_e32 v39, v39, v40
	s_nop 0
	v_readlane_b32 s61, v39, 63
	s_nop 1
	v_sub_f32_e32 v40, s61, v39
	v_fmac_f32_e32 v40, 0x3d800000, v38
	v_mov_b32_e32 v38, s99
	v_fmac_f32_e32 v38, s32, v64
	v_readlane_b32 s80, v26, 39
	v_readlane_b32 s3, v31, 55
	v_cndmask_b32_e64 v95, v40, v39, s[0:1]
	v_readlane_b32 s93, v26, 63
	global_store_dword v250, v95, s[100:101] offset:3584
	v_readlane_b32 s98, v27, 23
	v_fmac_f32_e32 v38, s80, v63
	v_readlane_b32 s99, v27, 47
	v_fmac_f32_e32 v38, s93, v62
	v_readlane_b32 s32, v28, 7
	v_fmac_f32_e32 v38, s98, v61
	v_readlane_b32 s80, v28, 31
	v_fmac_f32_e32 v38, s99, v60
	v_readlane_b32 s93, v28, 55
	v_fmac_f32_e32 v38, s32, v59
	v_readlane_b32 s98, v29, 15
	v_fmac_f32_e32 v38, s80, v58
	v_readlane_b32 s99, v29, 39
	v_fmac_f32_e32 v38, s93, v57
	v_readlane_b32 s32, v29, 63
	v_fmac_f32_e32 v38, s98, v56
	v_readlane_b32 s80, v30, 23
	v_fmac_f32_e32 v38, s99, v55
	v_readlane_b32 s93, v30, 47
	v_fmac_f32_e32 v38, s32, v54
	v_readlane_b32 s98, v31, 7
	v_fmac_f32_e32 v38, s80, v53
	v_fmac_f32_e32 v38, s93, v52
	v_fmac_f32_e32 v38, s98, v34
	v_readlane_b32 s2, v31, 31
; template <bool PHC>
; __device__ __forceinline__ void gla_pair(const KPD& kp, int l, int pair, unsigned char* lds, int tid, int lane, int wave, v4u& pz0, v4u& pz1, v4u& pw0, v4u& pw1, int next_pair) {
;     ...
;     for (int c = 0; c < 24; ++c) {
;         float pre = __int_as_float(__builtin_amdgcn_readlane(bvv, c));
; #pragma unroll
;         for (int r = 0; r < 16; ++r) pre += z[r] * __int_as_float(__builtin_amdgcn_readlane(wvv[(24 * r + c) >> 6], (24 * r + c) & 63));
;         const float la = (fminf(pre, 0.f) - __logf(1.f + __expf(-fabsf(pre)))) * (1.f / 16.f);
;         const float inc = wave_incl_scan(la);
;         const float total = __int_as_float(__builtin_amdgcn_readlane(__float_as_int(inc), 63));
;         bc[c] = dir ? (total - inc + la) : inc; tot[c] = total;
	s_nop 1
	v_pk_mul_f32 v[96:97], v[50:51], s[2:3]
	v_readlane_b32 s99, v32, 16
	v_add_f32_e32 v38, v38, v96
	v_add_f32_e32 v38, v38, v97
	v_min_f32_e32 v39, 0, v38
	v_mul_f32_e64 v38, |v38|, s72
	v_exp_f32_e32 v38, v38
	v_readlane_b32 s32, v26, 16
	v_add_f32_e32 v38, 1.0, v38
	v_cmp_gt_f32_e32 vcc, s78, v38
	s_nop 1
	v_cndmask_b32_e64 v40, 0, 32, vcc
	v_ldexp_f32 v38, v38, v40
	v_log_f32_e32 v38, v38
	s_nop 0
	v_mul_f32_e32 v40, 0x3f317217, v38
	v_fma_f32 v40, v38, s87, -v40
	v_fmac_f32_e32 v40, 0x3377d1cf, v38
	v_fmac_f32_e32 v40, 0x3f317217, v38
	v_cmp_lt_f32_e64 s[10:11], |v38|, s97
	s_nop 1
	v_cndmask_b32_e64 v38, v38, v40, s[10:11]
	v_cndmask_b32_e32 v40, 0, v222, vcc
	v_sub_f32_e32 v38, v38, v40
	v_sub_f32_e32 v38, v39, v38
	v_mul_f32_e32 v39, 0x3d800000, v38
	v_mov_b32_e32 v40, v35
	s_nop 0
	v_mov_b32_dpp v39, v39 row_shr:1 row_mask:0xf bank_mask:0xf bound_ctrl:1
	v_fmac_f32_e32 v39, 0x3d800000, v38
	s_nop 1
	v_add_f32_dpp v39, v39, v39 row_shr:2 row_mask:0xf bank_mask:0xf bound_ctrl:1
	s_nop 1
	v_add_f32_dpp v39, v39, v39 row_shr:4 row_mask:0xf bank_mask:0xf bound_ctrl:1
	s_nop 1
	v_add_f32_dpp v39, v39, v39 row_shr:8 row_mask:0xf bank_mask:0xf bound_ctrl:1
	s_nop 1
	v_mov_b32_dpp v40, v39 row_bcast:15 row_mask:0xa bank_mask:0xf
	v_add_f32_e32 v39, v39, v40
	v_mov_b32_e32 v40, v35
	s_nop 0
	v_mov_b32_dpp v40, v39 row_bcast:31 row_mask:0xc bank_mask:0xf
	v_add_f32_e32 v39, v39, v40
	s_nop 0
	v_readlane_b32 s62, v39, 63
	s_nop 1
	v_sub_f32_e32 v40, s62, v39
	v_fmac_f32_e32 v40, 0x3d800000, v38
	v_mov_b32_e32 v38, s99
	v_fmac_f32_e32 v38, s32, v64
	v_readlane_b32 s80, v26, 40
	v_readlane_b32 s3, v31, 56
	v_cndmask_b32_e64 v96, v40, v39, s[0:1]
	v_readlane_b32 s93, v27, 0
	global_store_dword v250, v96, s[100:101] offset:3840
	v_readlane_b32 s98, v27, 24
	v_fmac_f32_e32 v38, s80, v63
	v_readlane_b32 s99, v27, 48
	v_fmac_f32_e32 v38, s93, v62
	v_readlane_b32 s32, v28, 8
	v_fmac_f32_e32 v38, s98, v61
	v_readlane_b32 s80, v28, 32
	v_fmac_f32_e32 v38, s99, v60
	v_readlane_b32 s93, v28, 56
	v_fmac_f32_e32 v38, s32, v59
	v_readlane_b32 s98, v29, 16
	v_fmac_f32_e32 v38, s80, v58
	v_readlane_b32 s99, v29, 40
	v_fmac_f32_e32 v38, s93, v57
	v_readlane_b32 s32, v30, 0
	v_fmac_f32_e32 v38, s98, v56
	v_readlane_b32 s80, v30, 24
	v_fmac_f32_e32 v38, s99, v55
	v_readlane_b32 s93, v30, 48
	v_fmac_f32_e32 v38, s32, v54
	v_readlane_b32 s98, v31, 8
	v_fmac_f32_e32 v38, s80, v53
	v_fmac_f32_e32 v38, s93, v52
	v_fmac_f32_e32 v38, s98, v34
	v_readlane_b32 s2, v31, 32
	s_nop 1
	v_pk_mul_f32 v[98:99], v[50:51], s[2:3]
	v_readlane_b32 s99, v32, 17
	v_add_f32_e32 v38, v38, v98
	v_add_f32_e32 v38, v38, v99
	v_min_f32_e32 v39, 0, v38
	v_mul_f32_e64 v38, |v38|, s72
	v_exp_f32_e32 v38, v38
	v_readlane_b32 s32, v26, 17
	v_add_f32_e32 v38, 1.0, v38
	v_cmp_gt_f32_e32 vcc, s78, v38
	s_nop 1
	v_cndmask_b32_e64 v40, 0, 32, vcc
	v_ldexp_f32 v38, v38, v40
	v_log_f32_e32 v38, v38
	s_nop 0
	v_mul_f32_e32 v40, 0x3f317217, v38
	v_fma_f32 v40, v38, s87, -v40
	v_fmac_f32_e32 v40, 0x3377d1cf, v38
	v_fmac_f32_e32 v40, 0x3f317217, v38
	v_cmp_lt_f32_e64 s[10:11], |v38|, s97
	s_nop 1
	v_cndmask_b32_e64 v38, v38, v40, s[10:11]
	v_cndmask_b32_e32 v40, 0, v222, vcc
	v_sub_f32_e32 v38, v38, v40
	v_sub_f32_e32 v38, v39, v38
	v_mul_f32_e32 v39, 0x3d800000, v38
	v_mov_b32_e32 v40, v35
	s_nop 0
	v_mov_b32_dpp v39, v39 row_shr:1 row_mask:0xf bank_mask:0xf bound_ctrl:1
	v_fmac_f32_e32 v39, 0x3d800000, v38
	s_nop 1
	v_add_f32_dpp v39, v39, v39 row_shr:2 row_mask:0xf bank_mask:0xf bound_ctrl:1
	s_nop 1
	v_add_f32_dpp v39, v39, v39 row_shr:4 row_mask:0xf bank_mask:0xf bound_ctrl:1
	s_nop 1
	v_add_f32_dpp v39, v39, v39 row_shr:8 row_mask:0xf bank_mask:0xf bound_ctrl:1
	s_nop 1
	v_mov_b32_dpp v40, v39 row_bcast:15 row_mask:0xa bank_mask:0xf
	v_add_f32_e32 v39, v39, v40
	v_mov_b32_e32 v40, v35
	s_nop 0
	v_mov_b32_dpp v40, v39 row_bcast:31 row_mask:0xc bank_mask:0xf
	v_add_f32_e32 v39, v39, v40
	s_nop 0
	v_readlane_b32 s63, v39, 63
	s_nop 1
	v_sub_f32_e32 v40, s63, v39
	v_fmac_f32_e32 v40, 0x3d800000, v38
	v_mov_b32_e32 v38, s99
	v_fmac_f32_e32 v38, s32, v64
	v_readlane_b32 s80, v26, 41
	v_readlane_b32 s3, v31, 57
	v_cndmask_b32_e64 v97, v40, v39, s[0:1]
	v_readlane_b32 s93, v27, 1
	global_store_dword v251, v97, s[100:101]
	v_readlane_b32 s98, v27, 25
	v_fmac_f32_e32 v38, s80, v63
	v_readlane_b32 s99, v27, 49
	v_fmac_f32_e32 v38, s93, v62
	v_readlane_b32 s32, v28, 9
	v_fmac_f32_e32 v38, s98, v61
	v_readlane_b32 s80, v28, 33
	v_fmac_f32_e32 v38, s99, v60
	v_readlane_b32 s93, v28, 57
	v_fmac_f32_e32 v38, s32, v59
	v_readlane_b32 s98, v29, 17
	v_fmac_f32_e32 v38, s80, v58
	v_readlane_b32 s99, v29, 41
	v_fmac_f32_e32 v38, s93, v57
	v_readlane_b32 s32, v30, 1
	v_fmac_f32_e32 v38, s98, v56
	v_readlane_b32 s80, v30, 25
	v_fmac_f32_e32 v38, s99, v55
	v_readlane_b32 s93, v30, 49
	v_fmac_f32_e32 v38, s32, v54
	v_readlane_b32 s98, v31, 9
	v_fmac_f32_e32 v38, s80, v53
	v_fmac_f32_e32 v38, s93, v52
	v_fmac_f32_e32 v38, s98, v34
	v_readlane_b32 s2, v31, 33
	s_nop 1
	v_pk_mul_f32 v[98:99], v[50:51], s[2:3]
	v_readlane_b32 s99, v32, 18
	v_add_f32_e32 v38, v38, v98
	v_add_f32_e32 v38, v38, v99
	v_min_f32_e32 v39, 0, v38
	v_mul_f32_e64 v38, |v38|, s72
	v_exp_f32_e32 v38, v38
	v_readlane_b32 s32, v26, 18
	v_add_f32_e32 v38, 1.0, v38
	v_cmp_gt_f32_e32 vcc, s78, v38
	s_nop 1
	v_cndmask_b32_e64 v40, 0, 32, vcc
	v_ldexp_f32 v38, v38, v40
	v_log_f32_e32 v38, v38
	s_nop 0
	v_mul_f32_e32 v40, 0x3f317217, v38
	v_fma_f32 v40, v38, s87, -v40
	v_fmac_f32_e32 v40, 0x3377d1cf, v38
	v_fmac_f32_e32 v40, 0x3f317217, v38
	v_cmp_lt_f32_e64 s[10:11], |v38|, s97
	s_nop 1
	v_cndmask_b32_e64 v38, v38, v40, s[10:11]
	v_cndmask_b32_e32 v40, 0, v222, vcc
; template <bool PHC>
; __device__ __forceinline__ void gla_pair(const KPD& kp, int l, int pair, unsigned char* lds, int tid, int lane, int wave, v4u& pz0, v4u& pz1, v4u& pw0, v4u& pw1, int next_pair) {
;     ...
;     for (int c = 0; c < 24; ++c) {
;         float pre = __int_as_float(__builtin_amdgcn_readlane(bvv, c));
; #pragma unroll
;         for (int r = 0; r < 16; ++r) pre += z[r] * __int_as_float(__builtin_amdgcn_readlane(wvv[(24 * r + c) >> 6], (24 * r + c) & 63));
;         const float la = (fminf(pre, 0.f) - __logf(1.f + __expf(-fabsf(pre)))) * (1.f / 16.f);
;         const float inc = wave_incl_scan(la);
;         const float total = __int_as_float(__builtin_amdgcn_readlane(__float_as_int(inc), 63));
;         bc[c] = dir ? (total - inc + la) : inc; tot[c] = total;
	v_sub_f32_e32 v38, v38, v40
	v_sub_f32_e32 v38, v39, v38
	v_mul_f32_e32 v39, 0x3d800000, v38
	v_mov_b32_e32 v40, v35
	s_nop 0
	v_mov_b32_dpp v39, v39 row_shr:1 row_mask:0xf bank_mask:0xf bound_ctrl:1
	v_fmac_f32_e32 v39, 0x3d800000, v38
	s_nop 1
	v_add_f32_dpp v39, v39, v39 row_shr:2 row_mask:0xf bank_mask:0xf bound_ctrl:1
	s_nop 1
	v_add_f32_dpp v39, v39, v39 row_shr:4 row_mask:0xf bank_mask:0xf bound_ctrl:1
	s_nop 1
	v_add_f32_dpp v39, v39, v39 row_shr:8 row_mask:0xf bank_mask:0xf bound_ctrl:1
	s_nop 1
	v_mov_b32_dpp v40, v39 row_bcast:15 row_mask:0xa bank_mask:0xf
	v_add_f32_e32 v39, v39, v40
	v_mov_b32_e32 v40, v35
	s_nop 0
	v_mov_b32_dpp v40, v39 row_bcast:31 row_mask:0xc bank_mask:0xf
	v_add_f32_e32 v39, v39, v40
	s_nop 0
	v_readlane_b32 s64, v39, 63
	s_nop 1
	v_sub_f32_e32 v40, s64, v39
	v_fmac_f32_e32 v40, 0x3d800000, v38
	v_mov_b32_e32 v38, s99
	v_fmac_f32_e32 v38, s32, v64
	v_readlane_b32 s80, v26, 42
	v_readlane_b32 s3, v31, 58
	v_cndmask_b32_e64 v98, v40, v39, s[0:1]
	v_readlane_b32 s93, v27, 2
	global_store_dword v251, v98, s[100:101] offset:256
	v_readlane_b32 s98, v27, 26
	v_fmac_f32_e32 v38, s80, v63
	v_readlane_b32 s99, v27, 50
	v_fmac_f32_e32 v38, s93, v62
	v_readlane_b32 s32, v28, 10
	v_fmac_f32_e32 v38, s98, v61
	v_readlane_b32 s80, v28, 34
	v_fmac_f32_e32 v38, s99, v60
	v_readlane_b32 s93, v28, 58
	v_fmac_f32_e32 v38, s32, v59
	v_readlane_b32 s98, v29, 18
	v_fmac_f32_e32 v38, s80, v58
	v_readlane_b32 s99, v29, 42
	v_fmac_f32_e32 v38, s93, v57
	v_readlane_b32 s32, v30, 2
	v_fmac_f32_e32 v38, s98, v56
	v_readlane_b32 s80, v30, 26
	v_fmac_f32_e32 v38, s99, v55
	v_readlane_b32 s93, v30, 50
	v_fmac_f32_e32 v38, s32, v54
	v_readlane_b32 s98, v31, 10
	v_fmac_f32_e32 v38, s80, v53
	v_fmac_f32_e32 v38, s93, v52
	v_fmac_f32_e32 v38, s98, v34
	v_readlane_b32 s2, v31, 34
	s_nop 1
	v_pk_mul_f32 v[100:101], v[50:51], s[2:3]
	v_readlane_b32 s99, v32, 19
	v_add_f32_e32 v38, v38, v100
	v_add_f32_e32 v38, v38, v101
	v_min_f32_e32 v39, 0, v38
	v_mul_f32_e64 v38, |v38|, s72
	v_exp_f32_e32 v38, v38
	v_readlane_b32 s32, v26, 19
	v_add_f32_e32 v38, 1.0, v38
	v_cmp_gt_f32_e32 vcc, s78, v38
	s_nop 1
	v_cndmask_b32_e64 v40, 0, 32, vcc
	v_ldexp_f32 v38, v38, v40
	v_log_f32_e32 v38, v38
	s_nop 0
	v_mul_f32_e32 v40, 0x3f317217, v38
	v_fma_f32 v40, v38, s87, -v40
	v_fmac_f32_e32 v40, 0x3377d1cf, v38
	v_fmac_f32_e32 v40, 0x3f317217, v38
	v_cmp_lt_f32_e64 s[10:11], |v38|, s97
	s_nop 1
	v_cndmask_b32_e64 v38, v38, v40, s[10:11]
	v_cndmask_b32_e32 v40, 0, v222, vcc
	v_sub_f32_e32 v38, v38, v40
	v_sub_f32_e32 v38, v39, v38
	v_mul_f32_e32 v39, 0x3d800000, v38
	v_mov_b32_e32 v40, v35
	s_nop 0
	v_mov_b32_dpp v39, v39 row_shr:1 row_mask:0xf bank_mask:0xf bound_ctrl:1
	v_fmac_f32_e32 v39, 0x3d800000, v38
	s_nop 1
	v_add_f32_dpp v39, v39, v39 row_shr:2 row_mask:0xf bank_mask:0xf bound_ctrl:1
	s_nop 1
	v_add_f32_dpp v39, v39, v39 row_shr:4 row_mask:0xf bank_mask:0xf bound_ctrl:1
	s_nop 1
	v_add_f32_dpp v39, v39, v39 row_shr:8 row_mask:0xf bank_mask:0xf bound_ctrl:1
	s_nop 1
	v_mov_b32_dpp v40, v39 row_bcast:15 row_mask:0xa bank_mask:0xf
	v_add_f32_e32 v39, v39, v40
	v_mov_b32_e32 v40, v35
	s_nop 0
	v_mov_b32_dpp v40, v39 row_bcast:31 row_mask:0xc bank_mask:0xf
	v_add_f32_e32 v39, v39, v40
	s_nop 0
	v_readlane_b32 s65, v39, 63
	s_nop 1
	v_sub_f32_e32 v40, s65, v39
	v_fmac_f32_e32 v40, 0x3d800000, v38
	v_mov_b32_e32 v38, s99
	v_fmac_f32_e32 v38, s32, v64
	v_readlane_b32 s80, v26, 43
	v_readlane_b32 s3, v31, 59
	v_cndmask_b32_e64 v99, v40, v39, s[0:1]
	v_readlane_b32 s93, v27, 3
	global_store_dword v251, v99, s[100:101] offset:512
	v_readlane_b32 s98, v27, 27
	v_fmac_f32_e32 v38, s80, v63
	v_readlane_b32 s99, v27, 51
	v_fmac_f32_e32 v38, s93, v62
	v_readlane_b32 s32, v28, 11
	v_fmac_f32_e32 v38, s98, v61
	v_readlane_b32 s80, v28, 35
	v_fmac_f32_e32 v38, s99, v60
	v_readlane_b32 s93, v28, 59
	v_fmac_f32_e32 v38, s32, v59
	v_readlane_b32 s98, v29, 19
	v_fmac_f32_e32 v38, s80, v58
	v_readlane_b32 s99, v29, 43
	v_fmac_f32_e32 v38, s93, v57
	v_readlane_b32 s32, v30, 3
	v_fmac_f32_e32 v38, s98, v56
	v_readlane_b32 s80, v30, 27
	v_fmac_f32_e32 v38, s99, v55
	v_readlane_b32 s93, v30, 51
	v_fmac_f32_e32 v38, s32, v54
	v_readlane_b32 s98, v31, 11
	v_fmac_f32_e32 v38, s80, v53
	v_fmac_f32_e32 v38, s93, v52
	v_fmac_f32_e32 v38, s98, v34
	v_readlane_b32 s2, v31, 35
	s_nop 1
	v_pk_mul_f32 v[100:101], v[50:51], s[2:3]
	v_readlane_b32 s99, v32, 20
	v_add_f32_e32 v38, v38, v100
	v_add_f32_e32 v38, v38, v101
	v_min_f32_e32 v39, 0, v38
	v_mul_f32_e64 v38, |v38|, s72
	v_exp_f32_e32 v38, v38
	v_readlane_b32 s32, v26, 20
	v_add_f32_e32 v38, 1.0, v38
	v_cmp_gt_f32_e32 vcc, s78, v38
	s_nop 1
	v_cndmask_b32_e64 v40, 0, 32, vcc
	v_ldexp_f32 v38, v38, v40
	v_log_f32_e32 v38, v38
	s_nop 0
	v_mul_f32_e32 v40, 0x3f317217, v38
	v_fma_f32 v40, v38, s87, -v40
	v_fmac_f32_e32 v40, 0x3377d1cf, v38
	v_fmac_f32_e32 v40, 0x3f317217, v38
	v_cmp_lt_f32_e64 s[10:11], |v38|, s97
	s_nop 1
	v_cndmask_b32_e64 v38, v38, v40, s[10:11]
	v_cndmask_b32_e32 v40, 0, v222, vcc
	v_sub_f32_e32 v38, v38, v40
	v_sub_f32_e32 v38, v39, v38
	v_mul_f32_e32 v39, 0x3d800000, v38
	v_mov_b32_e32 v40, v35
	s_nop 0
	v_mov_b32_dpp v39, v39 row_shr:1 row_mask:0xf bank_mask:0xf bound_ctrl:1
	v_fmac_f32_e32 v39, 0x3d800000, v38
	s_nop 1
	v_add_f32_dpp v39, v39, v39 row_shr:2 row_mask:0xf bank_mask:0xf bound_ctrl:1
	s_nop 1
	v_add_f32_dpp v39, v39, v39 row_shr:4 row_mask:0xf bank_mask:0xf bound_ctrl:1
	s_nop 1
	v_add_f32_dpp v39, v39, v39 row_shr:8 row_mask:0xf bank_mask:0xf bound_ctrl:1
	s_nop 1
	v_mov_b32_dpp v40, v39 row_bcast:15 row_mask:0xa bank_mask:0xf
	v_add_f32_e32 v39, v39, v40
	v_mov_b32_e32 v40, v35
	s_nop 0
; template <bool PHC>
; __device__ __forceinline__ void gla_pair(const KPD& kp, int l, int pair, unsigned char* lds, int tid, int lane, int wave, v4u& pz0, v4u& pz1, v4u& pw0, v4u& pw1, int next_pair) {
;     ...
;     for (int c = 0; c < 24; ++c) {
;         float pre = __int_as_float(__builtin_amdgcn_readlane(bvv, c));
; #pragma unroll
;         for (int r = 0; r < 16; ++r) pre += z[r] * __int_as_float(__builtin_amdgcn_readlane(wvv[(24 * r + c) >> 6], (24 * r + c) & 63));
;         const float la = (fminf(pre, 0.f) - __logf(1.f + __expf(-fabsf(pre)))) * (1.f / 16.f);
;         const float inc = wave_incl_scan(la);
;         const float total = __int_as_float(__builtin_amdgcn_readlane(__float_as_int(inc), 63));
;         bc[c] = dir ? (total - inc + la) : inc; tot[c] = total;
	v_mov_b32_dpp v40, v39 row_bcast:31 row_mask:0xc bank_mask:0xf
	v_add_f32_e32 v39, v39, v40
	s_nop 0
	v_readlane_b32 s66, v39, 63
	s_nop 1
	v_sub_f32_e32 v40, s66, v39
	v_fmac_f32_e32 v40, 0x3d800000, v38
	v_mov_b32_e32 v38, s99
	v_fmac_f32_e32 v38, s32, v64
	v_readlane_b32 s80, v26, 44
	v_readlane_b32 s3, v31, 60
	v_cndmask_b32_e64 v100, v40, v39, s[0:1]
	v_readlane_b32 s93, v27, 4
	global_store_dword v251, v100, s[100:101] offset:768
	v_readlane_b32 s98, v27, 28
	v_fmac_f32_e32 v38, s80, v63
	v_readlane_b32 s99, v27, 52
	v_fmac_f32_e32 v38, s93, v62
	v_readlane_b32 s32, v28, 12
	v_fmac_f32_e32 v38, s98, v61
	v_readlane_b32 s80, v28, 36
	v_fmac_f32_e32 v38, s99, v60
	v_readlane_b32 s93, v28, 60
	v_fmac_f32_e32 v38, s32, v59
	v_readlane_b32 s98, v29, 20
	v_fmac_f32_e32 v38, s80, v58
	v_readlane_b32 s99, v29, 44
	v_fmac_f32_e32 v38, s93, v57
	v_readlane_b32 s32, v30, 4
	v_fmac_f32_e32 v38, s98, v56
	v_readlane_b32 s80, v30, 28
	v_fmac_f32_e32 v38, s99, v55
	v_readlane_b32 s93, v30, 52
	v_fmac_f32_e32 v38, s32, v54
	v_readlane_b32 s98, v31, 12
	v_fmac_f32_e32 v38, s80, v53
	v_fmac_f32_e32 v38, s93, v52
	v_fmac_f32_e32 v38, s98, v34
	v_readlane_b32 s2, v31, 36
	s_nop 1
	v_pk_mul_f32 v[102:103], v[50:51], s[2:3]
	v_readlane_b32 s99, v32, 21
	v_add_f32_e32 v38, v38, v102
	v_add_f32_e32 v38, v38, v103
	v_min_f32_e32 v39, 0, v38
	v_mul_f32_e64 v38, |v38|, s72
	v_exp_f32_e32 v38, v38
	v_readlane_b32 s32, v26, 21
	v_add_f32_e32 v38, 1.0, v38
	v_cmp_gt_f32_e32 vcc, s78, v38
	s_nop 1
	v_cndmask_b32_e64 v40, 0, 32, vcc
	v_ldexp_f32 v38, v38, v40
	v_log_f32_e32 v38, v38
	s_nop 0
	v_mul_f32_e32 v40, 0x3f317217, v38
	v_fma_f32 v40, v38, s87, -v40
	v_fmac_f32_e32 v40, 0x3377d1cf, v38
	v_fmac_f32_e32 v40, 0x3f317217, v38
	v_cmp_lt_f32_e64 s[10:11], |v38|, s97
	s_nop 1
	v_cndmask_b32_e64 v38, v38, v40, s[10:11]
	v_cndmask_b32_e32 v40, 0, v222, vcc
	v_sub_f32_e32 v38, v38, v40
	v_sub_f32_e32 v38, v39, v38
	v_mul_f32_e32 v39, 0x3d800000, v38
	v_mov_b32_e32 v40, v35
	s_nop 0
	v_mov_b32_dpp v39, v39 row_shr:1 row_mask:0xf bank_mask:0xf bound_ctrl:1
	v_fmac_f32_e32 v39, 0x3d800000, v38
	s_nop 1
	v_add_f32_dpp v39, v39, v39 row_shr:2 row_mask:0xf bank_mask:0xf bound_ctrl:1
	s_nop 1
	v_add_f32_dpp v39, v39, v39 row_shr:4 row_mask:0xf bank_mask:0xf bound_ctrl:1
	s_nop 1
	v_add_f32_dpp v39, v39, v39 row_shr:8 row_mask:0xf bank_mask:0xf bound_ctrl:1
	s_nop 1
	v_mov_b32_dpp v40, v39 row_bcast:15 row_mask:0xa bank_mask:0xf
	v_add_f32_e32 v39, v39, v40
	v_mov_b32_e32 v40, v35
	s_nop 0
	v_mov_b32_dpp v40, v39 row_bcast:31 row_mask:0xc bank_mask:0xf
	v_add_f32_e32 v39, v39, v40
	s_nop 0
	v_readlane_b32 s67, v39, 63
	s_nop 1
	v_sub_f32_e32 v40, s67, v39
	v_fmac_f32_e32 v40, 0x3d800000, v38
	v_mov_b32_e32 v38, s99
	v_fmac_f32_e32 v38, s32, v64
	v_readlane_b32 s80, v26, 45
	v_readlane_b32 s3, v31, 61
	v_cndmask_b32_e64 v101, v40, v39, s[0:1]
	v_readlane_b32 s93, v27, 5
	global_store_dword v251, v101, s[100:101] offset:1024
	v_readlane_b32 s98, v27, 29
	v_fmac_f32_e32 v38, s80, v63
	v_readlane_b32 s99, v27, 53
	v_fmac_f32_e32 v38, s93, v62
	v_readlane_b32 s32, v28, 13
	v_fmac_f32_e32 v38, s98, v61
	v_readlane_b32 s80, v28, 37
	v_fmac_f32_e32 v38, s99, v60
	v_readlane_b32 s93, v28, 61
	v_fmac_f32_e32 v38, s32, v59
	v_readlane_b32 s98, v29, 21
	v_fmac_f32_e32 v38, s80, v58
	v_readlane_b32 s99, v29, 45
	v_fmac_f32_e32 v38, s93, v57
	v_readlane_b32 s32, v30, 5
	v_fmac_f32_e32 v38, s98, v56
	v_readlane_b32 s80, v30, 29
	v_fmac_f32_e32 v38, s99, v55
	v_readlane_b32 s93, v30, 53
	v_fmac_f32_e32 v38, s32, v54
	v_readlane_b32 s98, v31, 13
	v_fmac_f32_e32 v38, s80, v53
	v_fmac_f32_e32 v38, s93, v52
	v_fmac_f32_e32 v38, s98, v34
	v_readlane_b32 s2, v31, 37
	s_nop 1
	v_pk_mul_f32 v[102:103], v[50:51], s[2:3]
	v_readlane_b32 s99, v32, 22
	v_add_f32_e32 v38, v38, v102
	v_add_f32_e32 v38, v38, v103
	v_min_f32_e32 v39, 0, v38
	v_mul_f32_e64 v38, |v38|, s72
	v_exp_f32_e32 v38, v38
	v_readlane_b32 s32, v26, 22
	v_add_f32_e32 v38, 1.0, v38
	v_cmp_gt_f32_e32 vcc, s78, v38
	s_nop 1
	v_cndmask_b32_e64 v40, 0, 32, vcc
	v_ldexp_f32 v38, v38, v40
	v_log_f32_e32 v38, v38
	s_nop 0
	v_mul_f32_e32 v40, 0x3f317217, v38
	v_fma_f32 v40, v38, s87, -v40
	v_fmac_f32_e32 v40, 0x3377d1cf, v38
	v_fmac_f32_e32 v40, 0x3f317217, v38
	v_cmp_lt_f32_e64 s[10:11], |v38|, s97
	s_nop 1
	v_cndmask_b32_e64 v38, v38, v40, s[10:11]
	v_cndmask_b32_e32 v40, 0, v222, vcc
	v_sub_f32_e32 v38, v38, v40
	v_sub_f32_e32 v38, v39, v38
	v_mul_f32_e32 v39, 0x3d800000, v38
	v_mov_b32_e32 v40, v35
	s_nop 0
	v_mov_b32_dpp v39, v39 row_shr:1 row_mask:0xf bank_mask:0xf bound_ctrl:1
	v_fmac_f32_e32 v39, 0x3d800000, v38
	s_nop 1
	v_add_f32_dpp v39, v39, v39 row_shr:2 row_mask:0xf bank_mask:0xf bound_ctrl:1
	s_nop 1
	v_add_f32_dpp v39, v39, v39 row_shr:4 row_mask:0xf bank_mask:0xf bound_ctrl:1
	s_nop 1
	v_add_f32_dpp v39, v39, v39 row_shr:8 row_mask:0xf bank_mask:0xf bound_ctrl:1
	s_nop 1
	v_mov_b32_dpp v40, v39 row_bcast:15 row_mask:0xa bank_mask:0xf
	v_add_f32_e32 v39, v39, v40
	v_mov_b32_e32 v40, v35
	s_nop 0
	v_mov_b32_dpp v40, v39 row_bcast:31 row_mask:0xc bank_mask:0xf
	v_add_f32_e32 v39, v39, v40
	s_nop 0
	v_readlane_b32 s68, v39, 63
	s_nop 1
	v_sub_f32_e32 v40, s68, v39
	v_fmac_f32_e32 v40, 0x3d800000, v38
	v_mov_b32_e32 v38, s99
	v_fmac_f32_e32 v38, s32, v64
	v_readlane_b32 s80, v26, 46
	v_readlane_b32 s3, v31, 62
	v_cndmask_b32_e64 v102, v40, v39, s[0:1]
	v_readlane_b32 s93, v27, 6
	global_store_dword v251, v102, s[100:101] offset:1280
	v_readlane_b32 s98, v27, 30
	v_fmac_f32_e32 v38, s80, v63
	v_readlane_b32 s99, v27, 54
	v_fmac_f32_e32 v38, s93, v62
	v_readlane_b32 s32, v28, 14
	v_fmac_f32_e32 v38, s98, v61
	v_readlane_b32 s80, v28, 38
; __device__ __forceinline__ unsigned pk2(float lo, float hi) { return cvtpk(lo, hi); }
; template <bool PHC>
; __device__ __forceinline__ void gla_pair(const KPD& kp, int l, int pair, unsigned char* lds, int tid, int lane, int wave, v4u& pz0, v4u& pz1, v4u& pw0, v4u& pw1, int next_pair) {
;     ...
;     for (int c = 0; c < 24; ++c) {
;         float pre = __int_as_float(__builtin_amdgcn_readlane(bvv, c));
; #pragma unroll
;         for (int r = 0; r < 16; ++r) pre += z[r] * __int_as_float(__builtin_amdgcn_readlane(wvv[(24 * r + c) >> 6], (24 * r + c) & 63));
;         const float la = (fminf(pre, 0.f) - __logf(1.f + __expf(-fabsf(pre)))) * (1.f / 16.f);
;         const float inc = wave_incl_scan(la);
;         const float total = __int_as_float(__builtin_amdgcn_readlane(__float_as_int(inc), 63));
;         bc[c] = dir ? (total - inc + la) : inc; tot[c] = total;
;     ...
;           for (int i = 0; i < 12; ++i) kw[i] = pk2(kv[2 * i] * __expf(tot[2 * i] - bc[2 * i]), kv[2 * i + 1] * __expf(tot[2 * i + 1] - bc[2 * i + 1]));
	v_fmac_f32_e32 v38, s99, v60
	v_readlane_b32 s93, v28, 62
	v_fmac_f32_e32 v38, s32, v59
	v_readlane_b32 s98, v29, 22
	v_fmac_f32_e32 v38, s80, v58
	v_readlane_b32 s99, v29, 46
	v_fmac_f32_e32 v38, s93, v57
	v_readlane_b32 s32, v30, 6
	v_fmac_f32_e32 v38, s98, v56
	v_readlane_b32 s80, v30, 30
	v_fmac_f32_e32 v38, s99, v55
	v_readlane_b32 s93, v30, 54
	v_fmac_f32_e32 v38, s32, v54
	v_readlane_b32 s98, v31, 14
	v_fmac_f32_e32 v38, s80, v53
	v_fmac_f32_e32 v38, s93, v52
	v_fmac_f32_e32 v38, s98, v34
	v_readlane_b32 s2, v31, 38
	s_nop 1
	v_pk_mul_f32 v[104:105], v[50:51], s[2:3]
	v_readlane_b32 s99, v32, 23
	v_add_f32_e32 v38, v38, v104
	v_add_f32_e32 v38, v38, v105
	v_min_f32_e32 v39, 0, v38
	v_mul_f32_e64 v38, |v38|, s72
	v_exp_f32_e32 v38, v38
	v_readlane_b32 s32, v26, 23
	v_add_f32_e32 v38, 1.0, v38
	v_cmp_gt_f32_e32 vcc, s78, v38
	s_nop 1
	v_cndmask_b32_e64 v40, 0, 32, vcc
	v_ldexp_f32 v38, v38, v40
	v_log_f32_e32 v38, v38
	s_nop 0
	v_mul_f32_e32 v40, 0x3f317217, v38
	v_fma_f32 v40, v38, s87, -v40
	v_fmac_f32_e32 v40, 0x3377d1cf, v38
	v_fmac_f32_e32 v40, 0x3f317217, v38
	v_cmp_lt_f32_e64 s[10:11], |v38|, s97
	s_nop 1
	v_cndmask_b32_e64 v38, v38, v40, s[10:11]
	v_cndmask_b32_e32 v40, 0, v222, vcc
	v_sub_f32_e32 v38, v38, v40
	v_sub_f32_e32 v38, v39, v38
	v_mul_f32_e32 v39, 0x3d800000, v38
	v_mov_b32_e32 v40, v35
	s_nop 0
	v_mov_b32_dpp v39, v39 row_shr:1 row_mask:0xf bank_mask:0xf bound_ctrl:1
	v_fmac_f32_e32 v39, 0x3d800000, v38
	s_nop 1
	v_add_f32_dpp v39, v39, v39 row_shr:2 row_mask:0xf bank_mask:0xf bound_ctrl:1
	s_nop 1
	v_add_f32_dpp v39, v39, v39 row_shr:4 row_mask:0xf bank_mask:0xf bound_ctrl:1
	s_nop 1
	v_add_f32_dpp v39, v39, v39 row_shr:8 row_mask:0xf bank_mask:0xf bound_ctrl:1
	s_nop 1
	v_mov_b32_dpp v40, v39 row_bcast:15 row_mask:0xa bank_mask:0xf
	v_add_f32_e32 v39, v39, v40
	v_mov_b32_e32 v40, v35
	s_nop 0
	v_mov_b32_dpp v40, v39 row_bcast:31 row_mask:0xc bank_mask:0xf
	v_add_f32_e32 v39, v39, v40
	s_nop 0
	v_readlane_b32 s69, v39, 63
	s_nop 1
	v_sub_f32_e32 v40, s69, v39
	v_fmac_f32_e32 v40, 0x3d800000, v38
	v_cndmask_b32_e64 v38, v40, v39, s[0:1]
	global_store_dword v251, v38, s[100:101] offset:1536
	v_mov_b32_e32 v39, s99
	v_fmac_f32_e32 v39, s32, v64
	v_readlane_b32 s80, v26, 47
	v_readlane_b32 s3, v31, 63
	v_sub_f32_e32 v38, s69, v38
	v_fmac_f32_e32 v39, s80, v63
	v_readlane_b32 s93, v27, 7
	v_mul_f32_e32 v38, 0x3fb8aa3b, v38
	v_exp_f32_e32 v38, v38
	v_readlane_b32 s98, v27, 31
	v_fmac_f32_e32 v39, s93, v62
	v_and_b32_e32 v62, 0xffff0000, v17
	v_fmac_f32_e32 v39, s98, v61
	v_readlane_b32 s99, v27, 55
	v_lshlrev_b32_e32 v61, 16, v17
	v_sub_f32_e32 v17, s29, v79
	v_fmac_f32_e32 v39, s99, v60
	v_readlane_b32 s32, v28, 15
	v_and_b32_e32 v60, 0xffff0000, v16
	v_mul_f32_e32 v17, 0x3fb8aa3b, v17
	v_fmac_f32_e32 v39, s32, v59
	v_readlane_b32 s80, v28, 39
	v_lshlrev_b32_e32 v59, 16, v16
	v_sub_f32_e32 v16, s30, v68
	v_fmac_f32_e32 v39, s80, v58
	v_readlane_b32 s93, v28, 63
	v_and_b32_e32 v58, 0xffff0000, v15
	v_mul_f32_e32 v16, 0x3fb8aa3b, v16
	v_fmac_f32_e32 v39, s93, v57
	v_readlane_b32 s98, v29, 23
	v_lshlrev_b32_e32 v57, 16, v15
	v_sub_f32_e32 v15, s36, v66
	v_fmac_f32_e32 v39, s98, v56
	v_readlane_b32 s99, v29, 47
	v_and_b32_e32 v56, 0xffff0000, v14
	v_mul_f32_e32 v15, 0x3fb8aa3b, v15
	v_fmac_f32_e32 v39, s99, v55
	v_readlane_b32 s32, v30, 7
	v_lshlrev_b32_e32 v55, 16, v14
	v_sub_f32_e32 v14, s54, v65
	v_fmac_f32_e32 v39, s32, v54
	v_readlane_b32 s80, v30, 31
	v_mul_f32_e32 v14, 0x3fb8aa3b, v14
	v_exp_f32_e32 v14, v14
	v_fmac_f32_e32 v39, s80, v53
	v_readlane_b32 s93, v30, 55
	v_exp_f32_e32 v15, v15
	v_exp_f32_e32 v16, v16
	v_fmac_f32_e32 v39, s93, v52
	v_readlane_b32 s98, v31, 15
	v_exp_f32_e32 v17, v17
	v_lshlrev_b32_e32 v52, 16, v43
	v_fmac_f32_e32 v39, s98, v34
	v_readlane_b32 s2, v31, 39
	v_and_b32_e32 v43, 0xffff0000, v43
	v_lshlrev_b32_e32 v53, 16, v44
	v_pk_mul_f32 v[50:51], v[50:51], s[2:3]
	v_and_b32_e32 v44, 0xffff0000, v44
	v_add_f32_e32 v34, v39, v50
	v_add_f32_e32 v34, v34, v51
	v_min_f32_e32 v39, 0, v34
	v_mul_f32_e64 v34, |v34|, s72
	v_exp_f32_e32 v34, v34
	v_lshlrev_b32_e32 v50, 16, v49
	v_and_b32_e32 v49, 0xffff0000, v49
	v_lshlrev_b32_e32 v51, 16, v42
	v_add_f32_e32 v34, 1.0, v34
	v_cmp_gt_f32_e32 vcc, s78, v34
	v_and_b32_e32 v42, 0xffff0000, v42
	v_lshlrev_b32_e32 v54, 16, v45
	v_cndmask_b32_e64 v40, 0, 32, vcc
	v_ldexp_f32 v34, v34, v40
	v_log_f32_e32 v34, v34
	v_and_b32_e32 v45, 0xffff0000, v45
	s_add_i32 s2, s52, s41
	s_mulk_i32 s2, 0x84
	v_mul_f32_e32 v40, 0x3f317217, v34
	v_fma_f32 v40, v34, s87, -v40
	v_fmac_f32_e32 v40, 0x3377d1cf, v34
	v_fmac_f32_e32 v40, 0x3f317217, v34
	v_cmp_lt_f32_e64 s[10:11], |v34|, s97
	s_add_i32 s2, s2, s53
	s_ashr_i32 s3, s2, 31
	v_cndmask_b32_e64 v34, v34, v40, s[10:11]
	v_cndmask_b32_e32 v40, 0, v222, vcc
	v_sub_f32_e32 v34, v34, v40
	v_sub_f32_e32 v34, v39, v34
	v_mul_f32_e32 v39, 0x3d800000, v34
	v_mov_b32_e32 v40, v35
	v_mul_f32_e32 v38, v38, v61
	v_mov_b32_dpp v39, v39 row_shr:1 row_mask:0xf bank_mask:0xf bound_ctrl:1
	v_fmac_f32_e32 v39, 0x3d800000, v34
	s_nop 1
	v_add_f32_dpp v39, v39, v39 row_shr:2 row_mask:0xf bank_mask:0xf bound_ctrl:1
	s_nop 1
	v_add_f32_dpp v39, v39, v39 row_shr:4 row_mask:0xf bank_mask:0xf bound_ctrl:1
	s_nop 1
	v_add_f32_dpp v39, v39, v39 row_shr:8 row_mask:0xf bank_mask:0xf bound_ctrl:1
	s_nop 1
	v_mov_b32_dpp v40, v39 row_bcast:15 row_mask:0xa bank_mask:0xf
	v_add_f32_e32 v39, v39, v40
	v_mov_b32_e32 v40, v35
	s_nop 0
; __device__ __forceinline__ unsigned pk2(float lo, float hi) { return cvtpk(lo, hi); }
; template <bool PHC>
; __device__ __forceinline__ void gla_pair(const KPD& kp, int l, int pair, unsigned char* lds, int tid, int lane, int wave, v4u& pz0, v4u& pz1, v4u& pw0, v4u& pw1, int next_pair) {
;     ...
;           for (int i = 0; i < 12; ++i) kw[i] = pk2(kv[2 * i] * __expf(tot[2 * i] - bc[2 * i]), kv[2 * i + 1] * __expf(tot[2 * i + 1] - bc[2 * i + 1]));
;           v4u* ko = (v4u*)(KE + (dir * 64 + lane) * 56 + d0);
; #pragma unroll
;           for (int i = 0; i < 3; ++i) ko[i] = (v4u){kw[4 * i], kw[4 * i + 1], kw[4 * i + 2], kw[4 * i + 3]}; }
;         if (lane == 0) {
; #pragma unroll
;             for (int c = 0; c < 24; ++c) DEC[stbase * 192 + h * 48 + d0 + c] = __expf(tot[c]);
;         }
	v_mov_b32_dpp v40, v39 row_bcast:31 row_mask:0xc bank_mask:0xf
	v_add_f32_e32 v39, v39, v40
	s_nop 0
	v_readlane_b32 s72, v39, 63
	s_nop 1
	v_sub_f32_e32 v40, s72, v39
	v_fmac_f32_e32 v40, 0x3d800000, v34
	v_cndmask_b32_e64 v34, v40, v39, s[0:1]
	global_store_dword v251, v34, s[100:101] offset:1792
	v_lshlrev_b32_e32 v39, 16, v46
	v_and_b32_e32 v40, 0xffff0000, v46
	v_mul_f32_e32 v14, v14, v39
	v_mul_f32_e32 v15, v15, v40
	v_cvt_pk_bf16_f32 v14, v14, v15
	v_sub_f32_e32 v15, s34, v67
	v_mul_f32_e32 v15, 0x3fb8aa3b, v15
	v_exp_f32_e32 v15, v15
	v_and_b32_e32 v46, 0xffff0000, v47
	v_mul_f32_e32 v16, v16, v46
	v_lshlrev_b32_e32 v47, 16, v48
	v_mul_f32_e32 v15, v15, v41
	v_cvt_pk_bf16_f32 v15, v15, v16
	v_sub_f32_e32 v16, s28, v69
	v_mul_f32_e32 v16, 0x3fb8aa3b, v16
	v_exp_f32_e32 v16, v16
	v_and_b32_e32 v48, 0xffff0000, v48
	v_mul_f32_e32 v17, v17, v48
	v_sub_f32_e32 v39, s35, v83
	v_mul_f32_e32 v16, v16, v47
	v_cvt_pk_bf16_f32 v16, v16, v17
	v_sub_f32_e32 v17, s31, v81
	v_mul_f32_e32 v17, 0x3fb8aa3b, v17
	v_mul_f32_e32 v39, 0x3fb8aa3b, v39
	v_exp_f32_e32 v17, v17
	v_exp_f32_e32 v39, v39
	v_sub_f32_e32 v40, s55, v87
	v_mul_f32_e32 v40, 0x3fb8aa3b, v40
	v_mul_f32_e32 v17, v17, v50
	v_mul_f32_e32 v39, v39, v49
	v_cvt_pk_bf16_f32 v17, v17, v39
	v_sub_f32_e32 v39, s37, v85
	v_mul_f32_e32 v39, 0x3fb8aa3b, v39
	v_exp_f32_e32 v39, v39
	v_exp_f32_e32 v40, v40
	v_sub_f32_e32 v34, s72, v34
	v_mul_f32_e32 v34, 0x3fb8aa3b, v34
	v_mul_f32_e32 v39, v39, v51
	v_mul_f32_e32 v40, v40, v42
	v_cvt_pk_bf16_f32 v42, v39, v40
	v_sub_f32_e32 v39, s56, v89
	v_sub_f32_e32 v40, s57, v91
	v_mul_f32_e32 v39, 0x3fb8aa3b, v39
	v_mul_f32_e32 v40, 0x3fb8aa3b, v40
	v_exp_f32_e32 v39, v39
	v_exp_f32_e32 v40, v40
	v_exp_f32_e32 v34, v34
	v_mul_f32_e32 v39, v39, v52
	v_mul_f32_e32 v40, v40, v43
	v_cvt_pk_bf16_f32 v43, v39, v40
	v_sub_f32_e32 v39, s59, v93
	v_sub_f32_e32 v40, s60, v94
	v_mul_f32_e32 v39, 0x3fb8aa3b, v39
	v_mul_f32_e32 v40, 0x3fb8aa3b, v40
	v_exp_f32_e32 v39, v39
	v_exp_f32_e32 v40, v40
	v_mul_f32_e32 v34, v34, v62
	v_cvt_pk_bf16_f32 v49, v38, v34
	v_mul_f32_e32 v39, v39, v53
	v_mul_f32_e32 v40, v40, v44
	v_cvt_pk_bf16_f32 v44, v39, v40
	v_sub_f32_e32 v39, s61, v95
	v_sub_f32_e32 v40, s62, v96
	v_mul_f32_e32 v39, 0x3fb8aa3b, v39
	v_mul_f32_e32 v40, 0x3fb8aa3b, v40
	v_exp_f32_e32 v39, v39
	v_exp_f32_e32 v40, v40
	v_mul_f32_e32 v39, v39, v54
	v_mul_f32_e32 v40, v40, v45
	v_cvt_pk_bf16_f32 v45, v39, v40
	v_sub_f32_e32 v39, s63, v97
	v_sub_f32_e32 v40, s64, v98
	v_mul_f32_e32 v39, 0x3fb8aa3b, v39
	v_mul_f32_e32 v40, 0x3fb8aa3b, v40
	v_exp_f32_e32 v39, v39
	v_exp_f32_e32 v40, v40
	v_mul_f32_e32 v39, v39, v55
	v_mul_f32_e32 v40, v40, v56
	v_cvt_pk_bf16_f32 v46, v39, v40
	v_sub_f32_e32 v39, s65, v99
	v_sub_f32_e32 v40, s66, v100
	v_mul_f32_e32 v39, 0x3fb8aa3b, v39
	v_mul_f32_e32 v40, 0x3fb8aa3b, v40
	v_exp_f32_e32 v39, v39
	v_exp_f32_e32 v40, v40
	v_mul_f32_e32 v39, v39, v57
	v_mul_f32_e32 v40, v40, v58
	v_cvt_pk_bf16_f32 v47, v39, v40
	v_sub_f32_e32 v39, s67, v101
	v_sub_f32_e32 v40, s68, v102
	v_mul_f32_e32 v39, 0x3fb8aa3b, v39
	v_mul_f32_e32 v40, 0x3fb8aa3b, v40
	v_exp_f32_e32 v39, v39
	v_exp_f32_e32 v40, v40
	v_mul_f32_e32 v39, v39, v59
	v_mul_f32_e32 v40, v40, v60
	v_cvt_pk_bf16_f32 v48, v39, v40
	ds_write_b128 v122, v[14:17] offset:13312
	ds_write_b128 v122, v[42:45] offset:13328
	ds_write_b128 v122, v[46:49] offset:13344
	s_and_saveexec_b64 s[10:11], s[4:5]
	s_cbranch_execz .LBB0_266
	s_mul_i32 s13, s2, 0x300
	s_mul_hi_i32 s12, s2, 0x300
	s_add_u32 s13, s50, s13
	s_addc_u32 s12, s49, s12
	s_lshl_b32 s49, s51, 2
	v_mul_f32_e32 v14, s54, v223
	v_mul_f32_e32 v15, s36, v223
	v_mul_f32_e32 v16, s34, v223
	v_mul_f32_e32 v17, s30, v223
	s_add_u32 s13, s13, s49
	v_exp_f32_e32 v14, v14
	v_exp_f32_e32 v15, v15
	v_exp_f32_e32 v16, v16
	v_exp_f32_e32 v17, v17
	s_addc_u32 s12, s12, 0
	s_lshl_b32 s49, s40, 2
	s_add_u32 s50, s13, s49
	s_addc_u32 s51, s12, 0
	v_mov_b32_e32 v34, 0x19b00000
	global_store_dwordx4 v34, v[14:17], s[50:51]
	s_add_u32 s12, s50, 0x19b00000
	s_addc_u32 s13, s51, 0
	v_mul_f32_e32 v14, s28, v223
	v_mul_f32_e32 v15, s29, v223
	v_mul_f32_e32 v16, s31, v223
	v_mul_f32_e32 v17, s35, v223
	v_exp_f32_e32 v14, v14
	v_exp_f32_e32 v15, v15
	v_exp_f32_e32 v16, v16
	v_exp_f32_e32 v17, v17
	global_store_dwordx4 v35, v[14:17], s[12:13] offset:16
	s_nop 1
	v_mul_f32_e32 v14, s37, v223
	v_mul_f32_e32 v15, s55, v223
	v_mul_f32_e32 v16, s56, v223
	v_mul_f32_e32 v17, s57, v223
	v_exp_f32_e32 v14, v14
	v_exp_f32_e32 v15, v15
	v_exp_f32_e32 v16, v16
	v_exp_f32_e32 v17, v17
	global_store_dwordx4 v35, v[14:17], s[12:13] offset:32
	s_nop 1
	v_mul_f32_e32 v14, s59, v223
	v_mul_f32_e32 v15, s60, v223
	v_mul_f32_e32 v16, s61, v223
	v_mul_f32_e32 v17, s62, v223
	v_exp_f32_e32 v14, v14
	v_exp_f32_e32 v15, v15
	v_exp_f32_e32 v16, v16
	v_exp_f32_e32 v17, v17
	global_store_dwordx4 v35, v[14:17], s[12:13] offset:48
	s_nop 1
	v_mul_f32_e32 v14, s63, v223
	v_mul_f32_e32 v15, s64, v223
	v_mul_f32_e32 v16, s65, v223
	v_mul_f32_e32 v17, s66, v223
	v_exp_f32_e32 v14, v14
	v_exp_f32_e32 v15, v15
	v_exp_f32_e32 v16, v16
	v_exp_f32_e32 v17, v17
	global_store_dwordx4 v35, v[14:17], s[12:13] offset:64
	s_nop 1
	v_mul_f32_e32 v14, s67, v223
	v_mul_f32_e32 v15, s68, v223
	v_mul_f32_e32 v16, s69, v223
	v_mul_f32_e32 v17, s72, v223
	v_exp_f32_e32 v14, v14
	v_exp_f32_e32 v15, v15
	v_exp_f32_e32 v16, v16
	v_exp_f32_e32 v17, v17
	global_store_dwordx4 v35, v[14:17], s[12:13] offset:80
